# GEMM K-loops: removed the adjacent s_setprio 0 / s_setprio 1 pairs between the two MFMA groups of each phase (on v33)
# speedup vs baseline: 1.0155x; 1.0082x over previous
; #define PG8_STAGE(bufoff, gbase, voff) do { _Pragma("unroll") for (int _i = 0; _i < 2; ++_i) \
;         __builtin_amdgcn_global_load_lds((const unsigned*)((const char*)(gbase) + (voff)[_i]), (PG8_LAS unsigned*)(lds + (bufoff) + ldsw + _i * 8192), 16, 0, 0); } while (0)
; #define PG8_LDA(dst, b, h) do { _Pragma("unroll") for (int m = 0; m < 4; ++m) _Pragma("unroll") for (int k = 0; k < 2; ++k) dst[m][k] = *(const PG8_LAS bf16x8*)(lds + PG8_SA(b, h) + aoff + m * 2048 + k * 1024); } while (0)
; #define PG8_LDB(dst, b, h) do { _Pragma("unroll") for (int n = 0; n < 2; ++n) _Pragma("unroll") for (int k = 0; k < 2; ++k) dst[n][k] = *(const PG8_LAS bf16x8*)(lds + PG8_SB(b, h) + boff + n * 2048 + k * 1024); } while (0)
; #define PG8_MMA(ai, bj, At, Bt) do { __builtin_amdgcn_s_setprio(1); _Pragma("unroll") for (int m = 0; m < 4; ++m) _Pragma("unroll") for (int n = 0; n < 2; ++n) _Pragma("unroll") for (int k = 0; k < 2; ++k) \
;         acc[ai][bj][m][n] = __builtin_amdgcn_mfma_f32_16x16x32_bf16(Bt[n][k], At[m][k], acc[ai][bj][m][n], 0, 0, 0); __builtin_amdgcn_s_setprio(0); } while (0)
; #define PG8_WAIT_V(n) asm volatile("s_waitcnt vmcnt(" #n ")" ::: "memory")
; #define PG8_WAIT_L(n) asm volatile("s_waitcnt lgkmcnt(" #n ")" ::: "memory")
; #define PG8_BAR __builtin_amdgcn_s_barrier()
; #define PG8_SCHED __builtin_amdgcn_sched_barrier(0)
; template <class Epi, class Sched, bool ALIGN_EPI = false, bool SP2 = false>
; __device__ __forceinline__ void gemm_phase(PG8_LAS unsigned char* lds, const Gemm g, const Sched& S, const Epi& E, const int wid0) {
;     ...
;             PG8_LDB(B0, 0, 0); PG8_LDB(B1, 0, 1); PG8_SCHED; PG8_LDA(At, 0, 0); PG8_STAGE(PG8_SA(1, 1), a1 + hstep, voffA);
;             PG8_WAIT_V(8); PG8_WAIT_L(0); PG8_BAR; PG8_MMA(0, 0, At, B0); PG8_MMA(0, 1, At, B1); PG8_BAR; PG8_SCHED;
;             PG8_LDA(At, 0, 1); PG8_STAGE(PG8_SB(0, 0), b2, voffB); PG8_STAGE(PG8_SB(0, 1), b2 + hstep, voffB); PG8_STAGE(PG8_SA(0, 0), a2, voffA);
;             PG8_WAIT_V(8); PG8_WAIT_L(0); PG8_BAR; PG8_MMA(1, 0, At, B0); PG8_MMA(1, 1, At, B1); PG8_BAR; PG8_SCHED;
.LBB0_484:
	s_add_u32 s8, s6, 0xfff80080
	s_addc_u32 s9, s7, -1
	s_add_i32 s47, 0, 0x10000
	s_cmp_eq_u32 s46, 28
	s_cselect_b32 s11, s3, s9
	s_cselect_b32 s10, s34, s8
	s_cselect_b32 s9, s35, s44
	s_cselect_b32 s8, s36, s37
	s_add_i32 s52, 0, 0x14000
	v_add_u32_e32 v156, s47, v161
	v_add_u32_e32 v178, s52, v161
	s_waitcnt lgkmcnt(0)
	ds_read_b128 v[128:131], v156
	ds_read_b128 v[148:151], v156 offset:1024
	ds_read_b128 v[152:155], v156 offset:2048
	ds_read_b128 v[156:159], v156 offset:3072
	ds_read_b128 v[166:169], v178
	ds_read_b128 v[170:173], v178 offset:1024
	ds_read_b128 v[174:177], v178 offset:2048
	ds_read_b128 v[178:181], v178 offset:3072
	v_lshl_add_u64 v[190:191], s[6:7], 0, v[144:145]
	s_add_i32 m0, s73, 0xc000
	ds_read_b128 v[182:185], v165
	ds_read_b128 v[186:189], v165 offset:1024
	ds_read_b128 v[202:205], v165 offset:2048
	ds_read_b128 v[206:209], v165 offset:3072
	ds_read_b128 v[210:213], v165 offset:4096
	ds_read_b128 v[214:217], v165 offset:5120
	ds_read_b128 v[218:221], v165 offset:6144
	ds_read_b128 v[222:225], v165 offset:7168
	global_load_lds_dwordx4 v[190:191], off
	v_lshl_add_u64 v[190:191], s[6:7], 0, v[146:147]
	s_add_i32 m0, s73, 0xe000
	s_nop 0
	global_load_lds_dwordx4 v[190:191], off
	s_waitcnt vmcnt(8)
	s_waitcnt lgkmcnt(0)
	s_barrier
	s_setprio 1
	s_waitcnt lgkmcnt(0)
	v_mfma_f32_16x16x32_bf16 v[124:127], v[128:131], v[182:185], v[124:127]
	v_mfma_f32_16x16x32_bf16 v[120:123], v[152:155], v[182:185], v[120:123]
	v_mfma_f32_16x16x32_bf16 v[108:111], v[128:131], v[202:205], v[108:111]
	v_mfma_f32_16x16x32_bf16 v[104:107], v[152:155], v[202:205], v[104:107]
	v_mfma_f32_16x16x32_bf16 v[92:95], v[128:131], v[210:213], v[92:95]
	v_mfma_f32_16x16x32_bf16 v[88:91], v[152:155], v[210:213], v[88:91]
	v_mfma_f32_16x16x32_bf16 v[76:79], v[128:131], v[218:221], v[76:79]
	v_mfma_f32_16x16x32_bf16 v[72:75], v[152:155], v[218:221], v[72:75]
	v_mfma_f32_16x16x32_bf16 v[124:127], v[148:151], v[186:189], v[124:127]
	v_mfma_f32_16x16x32_bf16 v[120:123], v[156:159], v[186:189], v[120:123]
	v_mfma_f32_16x16x32_bf16 v[108:111], v[148:151], v[206:209], v[108:111]
	v_mfma_f32_16x16x32_bf16 v[104:107], v[156:159], v[206:209], v[104:107]
	v_mfma_f32_16x16x32_bf16 v[92:95], v[148:151], v[214:217], v[92:95]
	v_mfma_f32_16x16x32_bf16 v[88:91], v[156:159], v[214:217], v[88:91]
	v_mfma_f32_16x16x32_bf16 v[76:79], v[148:151], v[222:225], v[76:79]
	v_mfma_f32_16x16x32_bf16 v[72:75], v[156:159], v[222:225], v[72:75]
	v_mfma_f32_16x16x32_bf16 v[116:119], v[166:169], v[182:185], v[116:119]
	v_mfma_f32_16x16x32_bf16 v[112:115], v[174:177], v[182:185], v[112:115]
	v_mfma_f32_16x16x32_bf16 v[100:103], v[166:169], v[202:205], v[100:103]
	v_mfma_f32_16x16x32_bf16 v[96:99], v[174:177], v[202:205], v[96:99]
	v_mfma_f32_16x16x32_bf16 v[84:87], v[166:169], v[210:213], v[84:87]
	v_mfma_f32_16x16x32_bf16 v[80:83], v[174:177], v[210:213], v[80:83]
	v_mfma_f32_16x16x32_bf16 v[68:71], v[166:169], v[218:221], v[68:71]
	v_mfma_f32_16x16x32_bf16 v[64:67], v[174:177], v[218:221], v[64:67]
	v_mfma_f32_16x16x32_bf16 v[116:119], v[170:173], v[186:189], v[116:119]
	v_mfma_f32_16x16x32_bf16 v[112:115], v[178:181], v[186:189], v[112:115]
	v_mfma_f32_16x16x32_bf16 v[100:103], v[170:173], v[206:209], v[100:103]
	v_mfma_f32_16x16x32_bf16 v[96:99], v[178:181], v[206:209], v[96:99]
	v_mfma_f32_16x16x32_bf16 v[84:87], v[170:173], v[214:217], v[84:87]
	v_mfma_f32_16x16x32_bf16 v[80:83], v[178:181], v[214:217], v[80:83]
	v_mfma_f32_16x16x32_bf16 v[68:71], v[170:173], v[222:225], v[68:71]
	v_mfma_f32_16x16x32_bf16 v[64:67], v[178:181], v[222:225], v[64:67]
	s_setprio 0
	s_barrier
	s_add_i32 s47, s47, s72
	v_lshl_add_u64 v[190:191], s[8:9], 0, v[136:137]
	s_mov_b32 m0, s47
	ds_read_b128 v[182:185], v165 offset:16384
	ds_read_b128 v[186:189], v165 offset:17408
	ds_read_b128 v[202:205], v165 offset:18432
	ds_read_b128 v[206:209], v165 offset:19456
	ds_read_b128 v[210:213], v165 offset:20480
	ds_read_b128 v[214:217], v165 offset:21504
	ds_read_b128 v[218:221], v165 offset:22528
	ds_read_b128 v[222:225], v165 offset:23552
	global_load_lds_dwordx4 v[190:191], off
	s_add_i32 m0, s47, 0x2000
	s_add_u32 s48, s8, 0x80000
	v_lshl_add_u64 v[194:195], s[8:9], 0, v[132:133]
	s_addc_u32 s49, s9, 0
	s_add_i32 s47, s52, s72
	global_load_lds_dwordx4 v[194:195], off
	v_lshl_add_u64 v[196:197], s[48:49], 0, v[136:137]
	s_mov_b32 m0, s47
	v_lshl_add_u64 v[226:227], s[10:11], 0, v[134:135]
	global_load_lds_dwordx4 v[196:197], off
	v_lshl_add_u64 v[196:197], s[48:49], 0, v[132:133]
	s_add_i32 m0, s47, 0x2000
	s_nop 0
	global_load_lds_dwordx4 v[196:197], off
	v_lshl_add_u64 v[196:197], s[10:11], 0, v[138:139]
	s_mov_b32 m0, s73
	s_nop 0
	global_load_lds_dwordx4 v[196:197], off
	s_mov_b32 m0, s78
	s_nop 0
	global_load_lds_dwordx4 v[226:227], off
	s_waitcnt vmcnt(8)
	s_waitcnt lgkmcnt(0)
	s_barrier
; #define PG8_STAGE(bufoff, gbase, voff) do { _Pragma("unroll") for (int _i = 0; _i < 2; ++_i) \
;         __builtin_amdgcn_global_load_lds((const unsigned*)((const char*)(gbase) + (voff)[_i]), (PG8_LAS unsigned*)(lds + (bufoff) + ldsw + _i * 8192), 16, 0, 0); } while (0)
; #define PG8_LDA(dst, b, h) do { _Pragma("unroll") for (int m = 0; m < 4; ++m) _Pragma("unroll") for (int k = 0; k < 2; ++k) dst[m][k] = *(const PG8_LAS bf16x8*)(lds + PG8_SA(b, h) + aoff + m * 2048 + k * 1024); } while (0)
; #define PG8_LDB(dst, b, h) do { _Pragma("unroll") for (int n = 0; n < 2; ++n) _Pragma("unroll") for (int k = 0; k < 2; ++k) dst[n][k] = *(const PG8_LAS bf16x8*)(lds + PG8_SB(b, h) + boff + n * 2048 + k * 1024); } while (0)
; #define PG8_MMA(ai, bj, At, Bt) do { __builtin_amdgcn_s_setprio(1); _Pragma("unroll") for (int m = 0; m < 4; ++m) _Pragma("unroll") for (int n = 0; n < 2; ++n) _Pragma("unroll") for (int k = 0; k < 2; ++k) \
;         acc[ai][bj][m][n] = __builtin_amdgcn_mfma_f32_16x16x32_bf16(Bt[n][k], At[m][k], acc[ai][bj][m][n], 0, 0, 0); __builtin_amdgcn_s_setprio(0); } while (0)
; #define PG8_WAIT_V(n) asm volatile("s_waitcnt vmcnt(" #n ")" ::: "memory")
; #define PG8_WAIT_L(n) asm volatile("s_waitcnt lgkmcnt(" #n ")" ::: "memory")
; #define PG8_BAR __builtin_amdgcn_s_barrier()
; #define PG8_SCHED __builtin_amdgcn_sched_barrier(0)
; template <class Epi, class Sched, bool ALIGN_EPI = false, bool SP2 = false>
; __device__ __forceinline__ void gemm_phase(PG8_LAS unsigned char* lds, const Gemm g, const Sched& S, const Epi& E, const int wid0) {
;     ...
;             PG8_WAIT_V(8); PG8_WAIT_L(0); PG8_BAR; PG8_MMA(1, 0, At, B0); PG8_MMA(1, 1, At, B1); PG8_BAR; PG8_SCHED;
;             PG8_LDB(B0, 1, 0); PG8_LDB(B1, 1, 1); PG8_SCHED; PG8_LDA(At, 1, 0); PG8_STAGE(PG8_SA(0, 1), a2 + hstep, voffA);
;             PG8_WAIT_V(8); PG8_WAIT_L(0); PG8_BAR; PG8_MMA(0, 0, At, B0); PG8_MMA(0, 1, At, B1); PG8_BAR; PG8_SCHED;
;             PG8_LDA(At, 1, 1); PG8_STAGE(PG8_SB(1, 0), b3, voffB); PG8_STAGE(PG8_SB(1, 1), b3 + hstep, voffB); PG8_STAGE(PG8_SA(1, 0), a3, voffA);
	s_setprio 1
	s_waitcnt lgkmcnt(0)
	v_mfma_f32_16x16x32_bf16 v[60:63], v[128:131], v[182:185], v[60:63]
	v_mfma_f32_16x16x32_bf16 v[56:59], v[152:155], v[182:185], v[56:59]
	v_mfma_f32_16x16x32_bf16 v[44:47], v[128:131], v[202:205], v[44:47]
	v_mfma_f32_16x16x32_bf16 v[40:43], v[152:155], v[202:205], v[40:43]
	v_mfma_f32_16x16x32_bf16 v[28:31], v[128:131], v[210:213], v[28:31]
	v_mfma_f32_16x16x32_bf16 v[24:27], v[152:155], v[210:213], v[24:27]
	v_mfma_f32_16x16x32_bf16 v[12:15], v[128:131], v[218:221], v[12:15]
	v_mfma_f32_16x16x32_bf16 v[8:11], v[152:155], v[218:221], v[8:11]
	v_mfma_f32_16x16x32_bf16 v[60:63], v[148:151], v[186:189], v[60:63]
	v_mfma_f32_16x16x32_bf16 v[56:59], v[156:159], v[186:189], v[56:59]
	v_mfma_f32_16x16x32_bf16 v[44:47], v[148:151], v[206:209], v[44:47]
	v_mfma_f32_16x16x32_bf16 v[40:43], v[156:159], v[206:209], v[40:43]
	v_mfma_f32_16x16x32_bf16 v[28:31], v[148:151], v[214:217], v[28:31]
	v_mfma_f32_16x16x32_bf16 v[24:27], v[156:159], v[214:217], v[24:27]
	v_mfma_f32_16x16x32_bf16 v[12:15], v[148:151], v[222:225], v[12:15]
	v_mfma_f32_16x16x32_bf16 v[8:11], v[156:159], v[222:225], v[8:11]
	v_mfma_f32_16x16x32_bf16 v[52:55], v[166:169], v[182:185], v[52:55]
	v_mfma_f32_16x16x32_bf16 v[48:51], v[174:177], v[182:185], v[48:51]
	v_mfma_f32_16x16x32_bf16 v[36:39], v[166:169], v[202:205], v[36:39]
	v_mfma_f32_16x16x32_bf16 v[32:35], v[174:177], v[202:205], v[32:35]
	v_mfma_f32_16x16x32_bf16 v[20:23], v[166:169], v[210:213], v[20:23]
	v_mfma_f32_16x16x32_bf16 v[16:19], v[174:177], v[210:213], v[16:19]
	v_mfma_f32_16x16x32_bf16 v[4:7], v[166:169], v[218:221], v[4:7]
	v_mfma_f32_16x16x32_bf16 v[0:3], v[174:177], v[218:221], v[0:3]
	v_mfma_f32_16x16x32_bf16 v[52:55], v[170:173], v[186:189], v[52:55]
	v_mfma_f32_16x16x32_bf16 v[48:51], v[178:181], v[186:189], v[48:51]
	v_mfma_f32_16x16x32_bf16 v[36:39], v[170:173], v[206:209], v[36:39]
	v_mfma_f32_16x16x32_bf16 v[32:35], v[178:181], v[206:209], v[32:35]
	v_mfma_f32_16x16x32_bf16 v[20:23], v[170:173], v[214:217], v[20:23]
	v_mfma_f32_16x16x32_bf16 v[16:19], v[178:181], v[214:217], v[16:19]
	v_mfma_f32_16x16x32_bf16 v[4:7], v[170:173], v[222:225], v[4:7]
	v_mfma_f32_16x16x32_bf16 v[0:3], v[178:181], v[222:225], v[0:3]
	s_setprio 0
	s_barrier
	s_add_i32 s47, 0, 0x18000
	s_add_i32 s48, 0, 0x1c000
	v_add_u32_e32 v156, s47, v161
	v_add_u32_e32 v178, s48, v161
	ds_read_b128 v[128:131], v156
	ds_read_b128 v[148:151], v156 offset:1024
	ds_read_b128 v[152:155], v156 offset:2048
	ds_read_b128 v[156:159], v156 offset:3072
	ds_read_b128 v[166:169], v178
	ds_read_b128 v[170:173], v178 offset:1024
	ds_read_b128 v[174:177], v178 offset:2048
	ds_read_b128 v[178:181], v178 offset:3072
	s_add_u32 s10, s10, 0x80000
	s_addc_u32 s11, s11, 0
	s_mov_b32 m0, s79
	v_lshl_add_u64 v[228:229], s[10:11], 0, v[138:139]
	ds_read_b128 v[182:185], v165 offset:32768
	ds_read_b128 v[186:189], v165 offset:33792
	ds_read_b128 v[202:205], v165 offset:34816
	ds_read_b128 v[206:209], v165 offset:35840
	ds_read_b128 v[210:213], v165 offset:36864
	ds_read_b128 v[214:217], v165 offset:37888
	ds_read_b128 v[218:221], v165 offset:38912
	ds_read_b128 v[222:225], v165 offset:39936
	global_load_lds_dwordx4 v[228:229], off
	v_lshl_add_u64 v[228:229], s[10:11], 0, v[134:135]
	s_mov_b32 m0, s38
	s_nop 0
	global_load_lds_dwordx4 v[228:229], off
	s_waitcnt vmcnt(8)
	s_waitcnt lgkmcnt(0)
	s_barrier
	s_setprio 1
	s_waitcnt lgkmcnt(0)
	v_mfma_f32_16x16x32_bf16 v[124:127], v[128:131], v[182:185], v[124:127]
	v_mfma_f32_16x16x32_bf16 v[120:123], v[152:155], v[182:185], v[120:123]
	v_mfma_f32_16x16x32_bf16 v[108:111], v[128:131], v[202:205], v[108:111]
	v_mfma_f32_16x16x32_bf16 v[104:107], v[152:155], v[202:205], v[104:107]
	v_mfma_f32_16x16x32_bf16 v[92:95], v[128:131], v[210:213], v[92:95]
	v_mfma_f32_16x16x32_bf16 v[88:91], v[152:155], v[210:213], v[88:91]
	v_mfma_f32_16x16x32_bf16 v[76:79], v[128:131], v[218:221], v[76:79]
	v_mfma_f32_16x16x32_bf16 v[72:75], v[152:155], v[218:221], v[72:75]
	v_mfma_f32_16x16x32_bf16 v[124:127], v[148:151], v[186:189], v[124:127]
	v_mfma_f32_16x16x32_bf16 v[120:123], v[156:159], v[186:189], v[120:123]
	v_mfma_f32_16x16x32_bf16 v[108:111], v[148:151], v[206:209], v[108:111]
	v_mfma_f32_16x16x32_bf16 v[104:107], v[156:159], v[206:209], v[104:107]
	v_mfma_f32_16x16x32_bf16 v[92:95], v[148:151], v[214:217], v[92:95]
	v_mfma_f32_16x16x32_bf16 v[88:91], v[156:159], v[214:217], v[88:91]
	v_mfma_f32_16x16x32_bf16 v[76:79], v[148:151], v[222:225], v[76:79]
	v_mfma_f32_16x16x32_bf16 v[72:75], v[156:159], v[222:225], v[72:75]
	v_mfma_f32_16x16x32_bf16 v[116:119], v[166:169], v[182:185], v[116:119]
	v_mfma_f32_16x16x32_bf16 v[112:115], v[174:177], v[182:185], v[112:115]
	v_mfma_f32_16x16x32_bf16 v[100:103], v[166:169], v[202:205], v[100:103]
	v_mfma_f32_16x16x32_bf16 v[96:99], v[174:177], v[202:205], v[96:99]
	v_mfma_f32_16x16x32_bf16 v[84:87], v[166:169], v[210:213], v[84:87]
	v_mfma_f32_16x16x32_bf16 v[80:83], v[174:177], v[210:213], v[80:83]
	v_mfma_f32_16x16x32_bf16 v[68:71], v[166:169], v[218:221], v[68:71]
	v_mfma_f32_16x16x32_bf16 v[64:67], v[174:177], v[218:221], v[64:67]
	v_mfma_f32_16x16x32_bf16 v[116:119], v[170:173], v[186:189], v[116:119]
	v_mfma_f32_16x16x32_bf16 v[112:115], v[178:181], v[186:189], v[112:115]
	v_mfma_f32_16x16x32_bf16 v[100:103], v[170:173], v[206:209], v[100:103]
	v_mfma_f32_16x16x32_bf16 v[96:99], v[178:181], v[206:209], v[96:99]
	v_mfma_f32_16x16x32_bf16 v[84:87], v[170:173], v[214:217], v[84:87]
	v_mfma_f32_16x16x32_bf16 v[80:83], v[178:181], v[214:217], v[80:83]
	v_mfma_f32_16x16x32_bf16 v[68:71], v[170:173], v[222:225], v[68:71]
	v_mfma_f32_16x16x32_bf16 v[64:67], v[178:181], v[222:225], v[64:67]
	s_setprio 0
	s_barrier
; #define PG8_STAGE(bufoff, gbase, voff) do { _Pragma("unroll") for (int _i = 0; _i < 2; ++_i) \
;         __builtin_amdgcn_global_load_lds((const unsigned*)((const char*)(gbase) + (voff)[_i]), (PG8_LAS unsigned*)(lds + (bufoff) + ldsw + _i * 8192), 16, 0, 0); } while (0)
; #define PG8_LDA(dst, b, h) do { _Pragma("unroll") for (int m = 0; m < 4; ++m) _Pragma("unroll") for (int k = 0; k < 2; ++k) dst[m][k] = *(const PG8_LAS bf16x8*)(lds + PG8_SA(b, h) + aoff + m * 2048 + k * 1024); } while (0)
; #define PG8_MMA(ai, bj, At, Bt) do { __builtin_amdgcn_s_setprio(1); _Pragma("unroll") for (int m = 0; m < 4; ++m) _Pragma("unroll") for (int n = 0; n < 2; ++n) _Pragma("unroll") for (int k = 0; k < 2; ++k) \
;         acc[ai][bj][m][n] = __builtin_amdgcn_mfma_f32_16x16x32_bf16(Bt[n][k], At[m][k], acc[ai][bj][m][n], 0, 0, 0); __builtin_amdgcn_s_setprio(0); } while (0)
; #define PG8_WAIT_V(n) asm volatile("s_waitcnt vmcnt(" #n ")" ::: "memory")
; #define PG8_WAIT_L(n) asm volatile("s_waitcnt lgkmcnt(" #n ")" ::: "memory")
; #define PG8_BAR __builtin_amdgcn_s_barrier()
; #define PG8_SCHED __builtin_amdgcn_sched_barrier(0)
; template <class Epi, class Sched, bool ALIGN_EPI = false, bool SP2 = false>
; __device__ __forceinline__ void gemm_phase(PG8_LAS unsigned char* lds, const Gemm g, const Sched& S, const Epi& E, const int wid0) {
;     ...
;             PG8_LDA(At, 1, 1); PG8_STAGE(PG8_SB(1, 0), b3, voffB); PG8_STAGE(PG8_SB(1, 1), b3 + hstep, voffB); PG8_STAGE(PG8_SA(1, 0), a3, voffA);
;             PG8_WAIT_V(8); PG8_WAIT_L(0); PG8_BAR; PG8_MMA(1, 0, At, B0); PG8_MMA(1, 1, At, B1); PG8_BAR; PG8_SCHED;
;     ...
;         if constexpr (ALIGN_EPI) { if (wr == 0) PG8_BAR; }
	s_add_i32 s10, s47, s72
	v_lshl_add_u64 v[190:191], v[190:191], 0, s[54:55]
	s_mov_b32 m0, s10
	ds_read_b128 v[182:185], v165 offset:49152
	ds_read_b128 v[186:189], v165 offset:50176
	ds_read_b128 v[202:205], v165 offset:51200
	ds_read_b128 v[206:209], v165 offset:52224
	ds_read_b128 v[210:213], v165 offset:53248
	ds_read_b128 v[214:217], v165 offset:54272
	ds_read_b128 v[218:221], v165 offset:55296
	ds_read_b128 v[222:225], v165 offset:56320
	global_load_lds_dwordx4 v[190:191], off
	s_add_i32 m0, s10, 0x2000
	s_add_u32 s8, s8, 0x80080
	v_lshl_add_u64 v[190:191], v[194:195], 0, s[54:55]
	s_addc_u32 s9, s9, 0
	s_add_i32 s10, s48, s72
	global_load_lds_dwordx4 v[190:191], off
	v_lshl_add_u64 v[190:191], s[8:9], 0, v[136:137]
	s_mov_b32 m0, s10
	s_nop 0
	global_load_lds_dwordx4 v[190:191], off
	v_lshl_add_u64 v[190:191], s[8:9], 0, v[132:133]
	s_add_i32 m0, s10, 0x2000
	s_nop 0
	global_load_lds_dwordx4 v[190:191], off
	v_lshl_add_u64 v[190:191], v[196:197], 0, s[54:55]
	s_mov_b32 m0, s39
	s_nop 0
	global_load_lds_dwordx4 v[190:191], off
	v_lshl_add_u64 v[190:191], v[226:227], 0, s[54:55]
	s_mov_b32 m0, s22
	s_nop 0
	global_load_lds_dwordx4 v[190:191], off
	s_waitcnt vmcnt(8)
	s_waitcnt lgkmcnt(0)
	s_barrier
	s_setprio 1
	s_waitcnt lgkmcnt(0)
	v_mfma_f32_16x16x32_bf16 v[60:63], v[128:131], v[182:185], v[60:63]
	v_mfma_f32_16x16x32_bf16 v[56:59], v[152:155], v[182:185], v[56:59]
	v_mfma_f32_16x16x32_bf16 v[44:47], v[128:131], v[202:205], v[44:47]
	v_mfma_f32_16x16x32_bf16 v[40:43], v[152:155], v[202:205], v[40:43]
	v_mfma_f32_16x16x32_bf16 v[28:31], v[128:131], v[210:213], v[28:31]
	v_mfma_f32_16x16x32_bf16 v[24:27], v[152:155], v[210:213], v[24:27]
	v_mfma_f32_16x16x32_bf16 v[12:15], v[128:131], v[218:221], v[12:15]
	v_mfma_f32_16x16x32_bf16 v[8:11], v[152:155], v[218:221], v[8:11]
	v_mfma_f32_16x16x32_bf16 v[60:63], v[148:151], v[186:189], v[60:63]
	v_mfma_f32_16x16x32_bf16 v[56:59], v[156:159], v[186:189], v[56:59]
	v_mfma_f32_16x16x32_bf16 v[44:47], v[148:151], v[206:209], v[44:47]
	v_mfma_f32_16x16x32_bf16 v[40:43], v[156:159], v[206:209], v[40:43]
	v_mfma_f32_16x16x32_bf16 v[28:31], v[148:151], v[214:217], v[28:31]
	v_mfma_f32_16x16x32_bf16 v[24:27], v[156:159], v[214:217], v[24:27]
	v_mfma_f32_16x16x32_bf16 v[12:15], v[148:151], v[222:225], v[12:15]
	v_mfma_f32_16x16x32_bf16 v[8:11], v[156:159], v[222:225], v[8:11]
	v_mfma_f32_16x16x32_bf16 v[52:55], v[166:169], v[182:185], v[52:55]
	v_mfma_f32_16x16x32_bf16 v[48:51], v[174:177], v[182:185], v[48:51]
	v_mfma_f32_16x16x32_bf16 v[36:39], v[166:169], v[202:205], v[36:39]
	v_mfma_f32_16x16x32_bf16 v[32:35], v[174:177], v[202:205], v[32:35]
	v_mfma_f32_16x16x32_bf16 v[20:23], v[166:169], v[210:213], v[20:23]
	v_mfma_f32_16x16x32_bf16 v[16:19], v[174:177], v[210:213], v[16:19]
	v_mfma_f32_16x16x32_bf16 v[4:7], v[166:169], v[218:221], v[4:7]
	v_mfma_f32_16x16x32_bf16 v[0:3], v[174:177], v[218:221], v[0:3]
	v_mfma_f32_16x16x32_bf16 v[52:55], v[170:173], v[186:189], v[52:55]
	v_mfma_f32_16x16x32_bf16 v[48:51], v[178:181], v[186:189], v[48:51]
	v_mfma_f32_16x16x32_bf16 v[36:39], v[170:173], v[206:209], v[36:39]
	v_mfma_f32_16x16x32_bf16 v[32:35], v[178:181], v[206:209], v[32:35]
	v_mfma_f32_16x16x32_bf16 v[20:23], v[170:173], v[214:217], v[20:23]
	v_mfma_f32_16x16x32_bf16 v[16:19], v[178:181], v[214:217], v[16:19]
	v_mfma_f32_16x16x32_bf16 v[4:7], v[170:173], v[222:225], v[4:7]
	v_mfma_f32_16x16x32_bf16 v[0:3], v[178:181], v[222:225], v[0:3]
	s_setprio 0
	s_barrier
	s_add_i32 s46, s46, 2
	s_add_u32 s6, s6, 0x100
	s_addc_u32 s7, s7, 0
	s_add_u32 s37, s37, 0x100
	s_addc_u32 s44, s44, 0
	s_cmp_gt_u32 s46, 29
	s_cbranch_scc0 .LBB0_484
	s_and_b64 vcc, exec, s[76:77]
	s_cbranch_vccz .LBB0_487
	s_barrier

; #define PG8_STAGE(bufoff, gbase, voff) do { _Pragma("unroll") for (int _i = 0; _i < 2; ++_i) \
;         __builtin_amdgcn_global_load_lds((const unsigned*)((const char*)(gbase) + (voff)[_i]), (PG8_LAS unsigned*)(lds + (bufoff) + ldsw + _i * 8192), 16, 0, 0); } while (0)
; #define PG8_LDA(dst, b, h) do { _Pragma("unroll") for (int m = 0; m < 4; ++m) _Pragma("unroll") for (int k = 0; k < 2; ++k) dst[m][k] = *(const PG8_LAS bf16x8*)(lds + PG8_SA(b, h) + aoff + m * 2048 + k * 1024); } while (0)
; #define PG8_LDB(dst, b, h) do { _Pragma("unroll") for (int n = 0; n < 2; ++n) _Pragma("unroll") for (int k = 0; k < 2; ++k) dst[n][k] = *(const PG8_LAS bf16x8*)(lds + PG8_SB(b, h) + boff + n * 2048 + k * 1024); } while (0)
; #define PG8_MMA(ai, bj, At, Bt) do { __builtin_amdgcn_s_setprio(1); _Pragma("unroll") for (int m = 0; m < 4; ++m) _Pragma("unroll") for (int n = 0; n < 2; ++n) _Pragma("unroll") for (int k = 0; k < 2; ++k) \
;         acc[ai][bj][m][n] = __builtin_amdgcn_mfma_f32_16x16x32_bf16(Bt[n][k], At[m][k], acc[ai][bj][m][n], 0, 0, 0); __builtin_amdgcn_s_setprio(0); } while (0)
; #define PG8_WAIT_V(n) asm volatile("s_waitcnt vmcnt(" #n ")" ::: "memory")
; #define PG8_WAIT_L(n) asm volatile("s_waitcnt lgkmcnt(" #n ")" ::: "memory")
; template <class Epi, class Sched, bool ALIGN_EPI = false, bool SP2 = false>
; __device__ __forceinline__ void gemm_phase(PG8_LAS unsigned char* lds, const Gemm g, const Sched& S, const Epi& E, const int wid0) {
;     ...
;             const bool last = (t == nt - 2);
;             const char* a1 = cA + (size_t)(t + 1) * kstep;
;             const char* a2 = last ? nA : cA + (size_t)(t + 2) * kstep; const char* b2 = last ? nB : cB + (size_t)(t + 2) * kstep;
;             const char* a3 = a2 + kstep; const char* b3 = b2 + kstep;
;             if (last && has_next) S.a_ready(nxt);
;             if constexpr (SP2) {
;             PG8_LDB(B0, 0, 0); PG8_LDB(B1, 0, 1); PG8_SCHED; PG8_LDA(At, 0, 0); PG8_STAGE(PG8_SA(1, 1), a1 + hstep, voffA);
;             PG8_WAIT_V(8); PG8_WAIT_L(0); PG8_BAR; PG8_MMA(0, 0, At, B0); PG8_MMA(0, 1, At, B1); PG8_BAR; PG8_SCHED;
;             PG8_LDA(At, 0, 1); PG8_STAGE(PG8_SB(0, 0), b2, voffB); PG8_STAGE(PG8_SB(0, 1), b2 + hstep, voffB); PG8_STAGE(PG8_SA(0, 0), a2, voffA);
;             PG8_WAIT_V(8); PG8_WAIT_L(0); PG8_BAR; PG8_MMA(1, 0, At, B0); PG8_MMA(1, 1, At, B1); PG8_BAR; PG8_SCHED;
.LBB0_822:
	s_add_u32 s34, s70, 0xfff80080
	s_addc_u32 s35, s71, -1
	s_add_i32 s56, 0, 0x10000
	s_cmp_eq_u32 s53, 28
	s_cselect_b32 s75, s31, s35
	s_cselect_b32 s74, s47, s34
	v_add_u32_e32 v145, s56, v143
	s_cselect_b32 s35, s13, s52
	s_cselect_b32 s34, s48, s49
	s_add_i32 s68, 0, 0x14000
	ds_read_b128 v[146:149], v145
	ds_read_b128 v[150:153], v145 offset:1024
	ds_read_b128 v[154:157], v145 offset:2048
	ds_read_b128 v[158:161], v145 offset:3072
	v_add_u32_e32 v145, s68, v143
	ds_read_b128 v[162:165], v145
	ds_read_b128 v[166:169], v145 offset:1024
	ds_read_b128 v[170:173], v145 offset:2048
	ds_read_b128 v[174:177], v145 offset:3072
	v_lshl_add_u64 v[190:191], s[70:71], 0, v[138:139]
	s_add_i32 m0, s3, 0xc000
	ds_read_b128 v[178:181], v144
	ds_read_b128 v[182:185], v144 offset:1024
	ds_read_b128 v[186:189], v144 offset:2048
	ds_read_b128 v[202:205], v144 offset:3072
	ds_read_b128 v[206:209], v144 offset:4096
	ds_read_b128 v[210:213], v144 offset:5120
	ds_read_b128 v[214:217], v144 offset:6144
	ds_read_b128 v[218:221], v144 offset:7168
	global_load_lds_dwordx4 v[190:191], off
	v_lshl_add_u64 v[190:191], s[70:71], 0, v[140:141]
	s_add_i32 m0, s3, 0xe000
	s_nop 0
	global_load_lds_dwordx4 v[190:191], off
	s_waitcnt vmcnt(8)
	s_waitcnt lgkmcnt(0)
	s_barrier
	s_setprio 1
	s_waitcnt lgkmcnt(0)
	v_mfma_f32_16x16x32_bf16 v[124:127], v[146:149], v[178:181], v[124:127]
	v_mfma_f32_16x16x32_bf16 v[120:123], v[154:157], v[178:181], v[120:123]
	v_mfma_f32_16x16x32_bf16 v[116:119], v[146:149], v[186:189], v[116:119]
	v_mfma_f32_16x16x32_bf16 v[108:111], v[154:157], v[186:189], v[108:111]
	v_mfma_f32_16x16x32_bf16 v[100:103], v[146:149], v[206:209], v[100:103]
	v_mfma_f32_16x16x32_bf16 v[92:95], v[154:157], v[206:209], v[92:95]
	v_mfma_f32_16x16x32_bf16 v[84:87], v[146:149], v[214:217], v[84:87]
	v_mfma_f32_16x16x32_bf16 v[76:79], v[154:157], v[214:217], v[76:79]
	v_mfma_f32_16x16x32_bf16 v[124:127], v[150:153], v[182:185], v[124:127]
	v_mfma_f32_16x16x32_bf16 v[120:123], v[158:161], v[182:185], v[120:123]
	v_mfma_f32_16x16x32_bf16 v[116:119], v[150:153], v[202:205], v[116:119]
	v_mfma_f32_16x16x32_bf16 v[108:111], v[158:161], v[202:205], v[108:111]
	v_mfma_f32_16x16x32_bf16 v[100:103], v[150:153], v[210:213], v[100:103]
	v_mfma_f32_16x16x32_bf16 v[92:95], v[158:161], v[210:213], v[92:95]
	v_mfma_f32_16x16x32_bf16 v[84:87], v[150:153], v[218:221], v[84:87]
	v_mfma_f32_16x16x32_bf16 v[76:79], v[158:161], v[218:221], v[76:79]
	v_mfma_f32_16x16x32_bf16 v[112:115], v[162:165], v[178:181], v[112:115]
	v_mfma_f32_16x16x32_bf16 v[104:107], v[170:173], v[178:181], v[104:107]
	v_mfma_f32_16x16x32_bf16 v[96:99], v[162:165], v[186:189], v[96:99]
	v_mfma_f32_16x16x32_bf16 v[88:91], v[170:173], v[186:189], v[88:91]
	v_mfma_f32_16x16x32_bf16 v[80:83], v[162:165], v[206:209], v[80:83]
	v_mfma_f32_16x16x32_bf16 v[72:75], v[170:173], v[206:209], v[72:75]
	v_mfma_f32_16x16x32_bf16 v[68:71], v[162:165], v[214:217], v[68:71]
	v_mfma_f32_16x16x32_bf16 v[64:67], v[170:173], v[214:217], v[64:67]
	v_mfma_f32_16x16x32_bf16 v[112:115], v[166:169], v[182:185], v[112:115]
	v_mfma_f32_16x16x32_bf16 v[104:107], v[174:177], v[182:185], v[104:107]
	v_mfma_f32_16x16x32_bf16 v[96:99], v[166:169], v[202:205], v[96:99]
	v_mfma_f32_16x16x32_bf16 v[88:91], v[174:177], v[202:205], v[88:91]
	v_mfma_f32_16x16x32_bf16 v[80:83], v[166:169], v[210:213], v[80:83]
	v_mfma_f32_16x16x32_bf16 v[72:75], v[174:177], v[210:213], v[72:75]
	v_mfma_f32_16x16x32_bf16 v[68:71], v[166:169], v[218:221], v[68:71]
	v_mfma_f32_16x16x32_bf16 v[64:67], v[174:177], v[218:221], v[64:67]
	s_setprio 0
	s_barrier
	s_add_i32 s56, s56, s2
	v_lshl_add_u64 v[190:191], s[34:35], 0, v[130:131]
	s_mov_b32 m0, s56
	ds_read_b128 v[178:181], v144 offset:16384
	ds_read_b128 v[182:185], v144 offset:17408
	ds_read_b128 v[186:189], v144 offset:18432
	ds_read_b128 v[202:205], v144 offset:19456
	ds_read_b128 v[206:209], v144 offset:20480
	ds_read_b128 v[210:213], v144 offset:21504
	ds_read_b128 v[214:217], v144 offset:22528
	ds_read_b128 v[218:221], v144 offset:23552
	global_load_lds_dwordx4 v[190:191], off
	s_add_i32 m0, s56, 0x2000
	s_add_u32 s56, s34, 0x80000
	v_lshl_add_u64 v[194:195], s[34:35], 0, v[134:135]
	s_addc_u32 s57, s35, 0
	s_add_i32 s68, s68, s2
	global_load_lds_dwordx4 v[194:195], off
	v_lshl_add_u64 v[196:197], s[56:57], 0, v[130:131]
	s_mov_b32 m0, s68
	v_lshl_add_u64 v[222:223], s[74:75], 0, v[132:133]
	global_load_lds_dwordx4 v[196:197], off
	v_lshl_add_u64 v[196:197], s[56:57], 0, v[134:135]
	s_add_i32 m0, s68, 0x2000
	s_nop 0
	global_load_lds_dwordx4 v[196:197], off
	v_lshl_add_u64 v[196:197], s[74:75], 0, v[128:129]
	s_mov_b32 m0, s3
	s_nop 0
	global_load_lds_dwordx4 v[196:197], off
	s_mov_b32 m0, s22
	s_nop 0
	global_load_lds_dwordx4 v[222:223], off
	s_waitcnt vmcnt(8)
	s_waitcnt lgkmcnt(0)
	s_barrier
; #define PG8_STAGE(bufoff, gbase, voff) do { _Pragma("unroll") for (int _i = 0; _i < 2; ++_i) \
;         __builtin_amdgcn_global_load_lds((const unsigned*)((const char*)(gbase) + (voff)[_i]), (PG8_LAS unsigned*)(lds + (bufoff) + ldsw + _i * 8192), 16, 0, 0); } while (0)
; #define PG8_LDA(dst, b, h) do { _Pragma("unroll") for (int m = 0; m < 4; ++m) _Pragma("unroll") for (int k = 0; k < 2; ++k) dst[m][k] = *(const PG8_LAS bf16x8*)(lds + PG8_SA(b, h) + aoff + m * 2048 + k * 1024); } while (0)
; #define PG8_LDB(dst, b, h) do { _Pragma("unroll") for (int n = 0; n < 2; ++n) _Pragma("unroll") for (int k = 0; k < 2; ++k) dst[n][k] = *(const PG8_LAS bf16x8*)(lds + PG8_SB(b, h) + boff + n * 2048 + k * 1024); } while (0)
; #define PG8_MMA(ai, bj, At, Bt) do { __builtin_amdgcn_s_setprio(1); _Pragma("unroll") for (int m = 0; m < 4; ++m) _Pragma("unroll") for (int n = 0; n < 2; ++n) _Pragma("unroll") for (int k = 0; k < 2; ++k) \
;         acc[ai][bj][m][n] = __builtin_amdgcn_mfma_f32_16x16x32_bf16(Bt[n][k], At[m][k], acc[ai][bj][m][n], 0, 0, 0); __builtin_amdgcn_s_setprio(0); } while (0)
; #define PG8_WAIT_V(n) asm volatile("s_waitcnt vmcnt(" #n ")" ::: "memory")
; #define PG8_WAIT_L(n) asm volatile("s_waitcnt lgkmcnt(" #n ")" ::: "memory")
; #define PG8_BAR __builtin_amdgcn_s_barrier()
; #define PG8_SCHED __builtin_amdgcn_sched_barrier(0)
; template <class Epi, class Sched, bool ALIGN_EPI = false, bool SP2 = false>
; __device__ __forceinline__ void gemm_phase(PG8_LAS unsigned char* lds, const Gemm g, const Sched& S, const Epi& E, const int wid0) {
;     ...
;             PG8_WAIT_V(8); PG8_WAIT_L(0); PG8_BAR; PG8_MMA(1, 0, At, B0); PG8_MMA(1, 1, At, B1); PG8_BAR; PG8_SCHED;
;             PG8_LDB(B0, 1, 0); PG8_LDB(B1, 1, 1); PG8_SCHED; PG8_LDA(At, 1, 0); PG8_STAGE(PG8_SA(0, 1), a2 + hstep, voffA);
;             PG8_WAIT_V(8); PG8_WAIT_L(0); PG8_BAR; PG8_MMA(0, 0, At, B0); PG8_MMA(0, 1, At, B1); PG8_BAR; PG8_SCHED;
	s_setprio 1
	s_waitcnt lgkmcnt(0)
	v_mfma_f32_16x16x32_bf16 v[60:63], v[146:149], v[178:181], v[60:63]
	v_mfma_f32_16x16x32_bf16 v[56:59], v[154:157], v[178:181], v[56:59]
	v_mfma_f32_16x16x32_bf16 v[52:55], v[146:149], v[186:189], v[52:55]
	v_mfma_f32_16x16x32_bf16 v[44:47], v[154:157], v[186:189], v[44:47]
	v_mfma_f32_16x16x32_bf16 v[36:39], v[146:149], v[206:209], v[36:39]
	v_mfma_f32_16x16x32_bf16 v[28:31], v[154:157], v[206:209], v[28:31]
	v_mfma_f32_16x16x32_bf16 v[20:23], v[146:149], v[214:217], v[20:23]
	v_mfma_f32_16x16x32_bf16 v[12:15], v[154:157], v[214:217], v[12:15]
	v_mfma_f32_16x16x32_bf16 v[60:63], v[150:153], v[182:185], v[60:63]
	v_mfma_f32_16x16x32_bf16 v[56:59], v[158:161], v[182:185], v[56:59]
	v_mfma_f32_16x16x32_bf16 v[52:55], v[150:153], v[202:205], v[52:55]
	v_mfma_f32_16x16x32_bf16 v[44:47], v[158:161], v[202:205], v[44:47]
	v_mfma_f32_16x16x32_bf16 v[36:39], v[150:153], v[210:213], v[36:39]
	v_mfma_f32_16x16x32_bf16 v[28:31], v[158:161], v[210:213], v[28:31]
	v_mfma_f32_16x16x32_bf16 v[20:23], v[150:153], v[218:221], v[20:23]
	v_mfma_f32_16x16x32_bf16 v[12:15], v[158:161], v[218:221], v[12:15]
	v_mfma_f32_16x16x32_bf16 v[48:51], v[162:165], v[178:181], v[48:51]
	v_mfma_f32_16x16x32_bf16 v[40:43], v[170:173], v[178:181], v[40:43]
	v_mfma_f32_16x16x32_bf16 v[32:35], v[162:165], v[186:189], v[32:35]
	v_mfma_f32_16x16x32_bf16 v[24:27], v[170:173], v[186:189], v[24:27]
	v_mfma_f32_16x16x32_bf16 v[16:19], v[162:165], v[206:209], v[16:19]
	v_mfma_f32_16x16x32_bf16 v[8:11], v[170:173], v[206:209], v[8:11]
	v_mfma_f32_16x16x32_bf16 v[4:7], v[162:165], v[214:217], v[4:7]
	v_mfma_f32_16x16x32_bf16 v[0:3], v[170:173], v[214:217], v[0:3]
	v_mfma_f32_16x16x32_bf16 v[48:51], v[166:169], v[182:185], v[48:51]
	v_mfma_f32_16x16x32_bf16 v[40:43], v[174:177], v[182:185], v[40:43]
	v_mfma_f32_16x16x32_bf16 v[32:35], v[166:169], v[202:205], v[32:35]
	v_mfma_f32_16x16x32_bf16 v[24:27], v[174:177], v[202:205], v[24:27]
	v_mfma_f32_16x16x32_bf16 v[16:19], v[166:169], v[210:213], v[16:19]
	v_mfma_f32_16x16x32_bf16 v[8:11], v[174:177], v[210:213], v[8:11]
	v_mfma_f32_16x16x32_bf16 v[4:7], v[166:169], v[218:221], v[4:7]
	v_mfma_f32_16x16x32_bf16 v[0:3], v[174:177], v[218:221], v[0:3]
	s_setprio 0
	s_barrier
	s_add_i32 s68, 0, 0x18000
	v_add_u32_e32 v145, s68, v143
	s_add_i32 s72, 0, 0x1c000
	ds_read_b128 v[146:149], v145
	ds_read_b128 v[150:153], v145 offset:1024
	ds_read_b128 v[154:157], v145 offset:2048
	ds_read_b128 v[158:161], v145 offset:3072
	v_add_u32_e32 v145, s72, v143
	ds_read_b128 v[162:165], v145
	ds_read_b128 v[166:169], v145 offset:1024
	ds_read_b128 v[170:173], v145 offset:2048
	ds_read_b128 v[174:177], v145 offset:3072
	s_add_u32 s56, s74, 0x80000
	s_addc_u32 s57, s75, 0
	s_mov_b32 m0, s23
	v_lshl_add_u64 v[224:225], s[56:57], 0, v[128:129]
	ds_read_b128 v[178:181], v144 offset:32768
	ds_read_b128 v[182:185], v144 offset:33792
	ds_read_b128 v[186:189], v144 offset:34816
	ds_read_b128 v[202:205], v144 offset:35840
	ds_read_b128 v[206:209], v144 offset:36864
	ds_read_b128 v[210:213], v144 offset:37888
	ds_read_b128 v[214:217], v144 offset:38912
	ds_read_b128 v[218:221], v144 offset:39936
	global_load_lds_dwordx4 v[224:225], off
	v_lshl_add_u64 v[224:225], s[56:57], 0, v[132:133]
	s_mov_b32 m0, s38
	s_nop 0
	global_load_lds_dwordx4 v[224:225], off
	s_waitcnt vmcnt(8)
	s_waitcnt lgkmcnt(0)
	s_barrier
	s_setprio 1
	s_waitcnt lgkmcnt(0)
	v_mfma_f32_16x16x32_bf16 v[124:127], v[146:149], v[178:181], v[124:127]
	v_mfma_f32_16x16x32_bf16 v[120:123], v[154:157], v[178:181], v[120:123]
	v_mfma_f32_16x16x32_bf16 v[116:119], v[146:149], v[186:189], v[116:119]
	v_mfma_f32_16x16x32_bf16 v[108:111], v[154:157], v[186:189], v[108:111]
	v_mfma_f32_16x16x32_bf16 v[100:103], v[146:149], v[206:209], v[100:103]
	v_mfma_f32_16x16x32_bf16 v[92:95], v[154:157], v[206:209], v[92:95]
	v_mfma_f32_16x16x32_bf16 v[84:87], v[146:149], v[214:217], v[84:87]
	v_mfma_f32_16x16x32_bf16 v[76:79], v[154:157], v[214:217], v[76:79]
	v_mfma_f32_16x16x32_bf16 v[124:127], v[150:153], v[182:185], v[124:127]
	v_mfma_f32_16x16x32_bf16 v[120:123], v[158:161], v[182:185], v[120:123]
	v_mfma_f32_16x16x32_bf16 v[116:119], v[150:153], v[202:205], v[116:119]
	v_mfma_f32_16x16x32_bf16 v[108:111], v[158:161], v[202:205], v[108:111]
	v_mfma_f32_16x16x32_bf16 v[100:103], v[150:153], v[210:213], v[100:103]
	v_mfma_f32_16x16x32_bf16 v[92:95], v[158:161], v[210:213], v[92:95]
	v_mfma_f32_16x16x32_bf16 v[84:87], v[150:153], v[218:221], v[84:87]
	v_mfma_f32_16x16x32_bf16 v[76:79], v[158:161], v[218:221], v[76:79]
	v_mfma_f32_16x16x32_bf16 v[112:115], v[162:165], v[178:181], v[112:115]
	v_mfma_f32_16x16x32_bf16 v[104:107], v[170:173], v[178:181], v[104:107]
	v_mfma_f32_16x16x32_bf16 v[96:99], v[162:165], v[186:189], v[96:99]
	v_mfma_f32_16x16x32_bf16 v[88:91], v[170:173], v[186:189], v[88:91]
	v_mfma_f32_16x16x32_bf16 v[80:83], v[162:165], v[206:209], v[80:83]
	v_mfma_f32_16x16x32_bf16 v[72:75], v[170:173], v[206:209], v[72:75]
	v_mfma_f32_16x16x32_bf16 v[68:71], v[162:165], v[214:217], v[68:71]
	v_mfma_f32_16x16x32_bf16 v[64:67], v[170:173], v[214:217], v[64:67]
	v_mfma_f32_16x16x32_bf16 v[112:115], v[166:169], v[182:185], v[112:115]
	v_mfma_f32_16x16x32_bf16 v[104:107], v[174:177], v[182:185], v[104:107]
	v_mfma_f32_16x16x32_bf16 v[96:99], v[166:169], v[202:205], v[96:99]
	v_mfma_f32_16x16x32_bf16 v[88:91], v[174:177], v[202:205], v[88:91]
	v_mfma_f32_16x16x32_bf16 v[80:83], v[166:169], v[210:213], v[80:83]
	v_mfma_f32_16x16x32_bf16 v[72:75], v[174:177], v[210:213], v[72:75]
	v_mfma_f32_16x16x32_bf16 v[68:71], v[166:169], v[218:221], v[68:71]
	v_mfma_f32_16x16x32_bf16 v[64:67], v[174:177], v[218:221], v[64:67]
	s_setprio 0
	s_barrier
; #define PG8_STAGE(bufoff, gbase, voff) do { _Pragma("unroll") for (int _i = 0; _i < 2; ++_i) \
;         __builtin_amdgcn_global_load_lds((const unsigned*)((const char*)(gbase) + (voff)[_i]), (PG8_LAS unsigned*)(lds + (bufoff) + ldsw + _i * 8192), 16, 0, 0); } while (0)
; #define PG8_LDA(dst, b, h) do { _Pragma("unroll") for (int m = 0; m < 4; ++m) _Pragma("unroll") for (int k = 0; k < 2; ++k) dst[m][k] = *(const PG8_LAS bf16x8*)(lds + PG8_SA(b, h) + aoff + m * 2048 + k * 1024); } while (0)
; #define PG8_MMA(ai, bj, At, Bt) do { __builtin_amdgcn_s_setprio(1); _Pragma("unroll") for (int m = 0; m < 4; ++m) _Pragma("unroll") for (int n = 0; n < 2; ++n) _Pragma("unroll") for (int k = 0; k < 2; ++k) \
;         acc[ai][bj][m][n] = __builtin_amdgcn_mfma_f32_16x16x32_bf16(Bt[n][k], At[m][k], acc[ai][bj][m][n], 0, 0, 0); __builtin_amdgcn_s_setprio(0); } while (0)
; #define PG8_WAIT_V(n) asm volatile("s_waitcnt vmcnt(" #n ")" ::: "memory")
; #define PG8_WAIT_L(n) asm volatile("s_waitcnt lgkmcnt(" #n ")" ::: "memory")
; #define PG8_BAR __builtin_amdgcn_s_barrier()
; #define PG8_SCHED __builtin_amdgcn_sched_barrier(0)
; template <class Epi, class Sched, bool ALIGN_EPI = false, bool SP2 = false>
; __device__ __forceinline__ void gemm_phase(PG8_LAS unsigned char* lds, const Gemm g, const Sched& S, const Epi& E, const int wid0) {
;     ...
;             PG8_LDA(At, 1, 1); PG8_STAGE(PG8_SB(1, 0), b3, voffB); PG8_STAGE(PG8_SB(1, 1), b3 + hstep, voffB); PG8_STAGE(PG8_SA(1, 0), a3, voffA);
;             PG8_WAIT_V(8); PG8_WAIT_L(0); PG8_BAR; PG8_MMA(1, 0, At, B0); PG8_MMA(1, 1, At, B1); PG8_BAR; PG8_SCHED;
;     ...
;         if constexpr (ALIGN_EPI) { if (wr == 0) PG8_BAR; }
	s_add_i32 s56, s68, s2
	v_lshl_add_u64 v[190:191], v[190:191], 0, s[54:55]
	s_mov_b32 m0, s56
	ds_read_b128 v[178:181], v144 offset:49152
	ds_read_b128 v[182:185], v144 offset:50176
	ds_read_b128 v[186:189], v144 offset:51200
	ds_read_b128 v[202:205], v144 offset:52224
	ds_read_b128 v[206:209], v144 offset:53248
	ds_read_b128 v[210:213], v144 offset:54272
	ds_read_b128 v[214:217], v144 offset:55296
	ds_read_b128 v[218:221], v144 offset:56320
	global_load_lds_dwordx4 v[190:191], off
	s_add_i32 m0, s56, 0x2000
	s_add_u32 s34, s34, 0x80080
	v_lshl_add_u64 v[190:191], v[194:195], 0, s[54:55]
	s_addc_u32 s35, s35, 0
	s_add_i32 s56, s72, s2
	global_load_lds_dwordx4 v[190:191], off
	v_lshl_add_u64 v[190:191], s[34:35], 0, v[130:131]
	s_mov_b32 m0, s56
	s_nop 0
	global_load_lds_dwordx4 v[190:191], off
	v_lshl_add_u64 v[190:191], s[34:35], 0, v[134:135]
	s_add_i32 m0, s56, 0x2000
	s_nop 0
	global_load_lds_dwordx4 v[190:191], off
	v_lshl_add_u64 v[190:191], v[196:197], 0, s[54:55]
	s_mov_b32 m0, s39
	s_nop 0
	global_load_lds_dwordx4 v[190:191], off
	v_lshl_add_u64 v[190:191], v[222:223], 0, s[54:55]
	s_mov_b32 m0, s40
	s_nop 0
	global_load_lds_dwordx4 v[190:191], off
	s_waitcnt vmcnt(8)
	s_waitcnt lgkmcnt(0)
	s_barrier
	s_setprio 1
	s_waitcnt lgkmcnt(0)
	v_mfma_f32_16x16x32_bf16 v[60:63], v[146:149], v[178:181], v[60:63]
	v_mfma_f32_16x16x32_bf16 v[56:59], v[154:157], v[178:181], v[56:59]
	v_mfma_f32_16x16x32_bf16 v[52:55], v[146:149], v[186:189], v[52:55]
	v_mfma_f32_16x16x32_bf16 v[44:47], v[154:157], v[186:189], v[44:47]
	v_mfma_f32_16x16x32_bf16 v[36:39], v[146:149], v[206:209], v[36:39]
	v_mfma_f32_16x16x32_bf16 v[28:31], v[154:157], v[206:209], v[28:31]
	v_mfma_f32_16x16x32_bf16 v[20:23], v[146:149], v[214:217], v[20:23]
	v_mfma_f32_16x16x32_bf16 v[12:15], v[154:157], v[214:217], v[12:15]
	v_mfma_f32_16x16x32_bf16 v[60:63], v[150:153], v[182:185], v[60:63]
	v_mfma_f32_16x16x32_bf16 v[56:59], v[158:161], v[182:185], v[56:59]
	v_mfma_f32_16x16x32_bf16 v[52:55], v[150:153], v[202:205], v[52:55]
	v_mfma_f32_16x16x32_bf16 v[44:47], v[158:161], v[202:205], v[44:47]
	v_mfma_f32_16x16x32_bf16 v[36:39], v[150:153], v[210:213], v[36:39]
	v_mfma_f32_16x16x32_bf16 v[28:31], v[158:161], v[210:213], v[28:31]
	v_mfma_f32_16x16x32_bf16 v[20:23], v[150:153], v[218:221], v[20:23]
	v_mfma_f32_16x16x32_bf16 v[12:15], v[158:161], v[218:221], v[12:15]
	v_mfma_f32_16x16x32_bf16 v[48:51], v[162:165], v[178:181], v[48:51]
	v_mfma_f32_16x16x32_bf16 v[40:43], v[170:173], v[178:181], v[40:43]
	v_mfma_f32_16x16x32_bf16 v[32:35], v[162:165], v[186:189], v[32:35]
	v_mfma_f32_16x16x32_bf16 v[24:27], v[170:173], v[186:189], v[24:27]
	v_mfma_f32_16x16x32_bf16 v[16:19], v[162:165], v[206:209], v[16:19]
	v_mfma_f32_16x16x32_bf16 v[8:11], v[170:173], v[206:209], v[8:11]
	v_mfma_f32_16x16x32_bf16 v[4:7], v[162:165], v[214:217], v[4:7]
	v_mfma_f32_16x16x32_bf16 v[0:3], v[170:173], v[214:217], v[0:3]
	v_mfma_f32_16x16x32_bf16 v[48:51], v[166:169], v[182:185], v[48:51]
	v_mfma_f32_16x16x32_bf16 v[40:43], v[174:177], v[182:185], v[40:43]
	v_mfma_f32_16x16x32_bf16 v[32:35], v[166:169], v[202:205], v[32:35]
	v_mfma_f32_16x16x32_bf16 v[24:27], v[174:177], v[202:205], v[24:27]
	v_mfma_f32_16x16x32_bf16 v[16:19], v[166:169], v[210:213], v[16:19]
	v_mfma_f32_16x16x32_bf16 v[8:11], v[174:177], v[210:213], v[8:11]
	v_mfma_f32_16x16x32_bf16 v[4:7], v[166:169], v[218:221], v[4:7]
	v_mfma_f32_16x16x32_bf16 v[0:3], v[174:177], v[218:221], v[0:3]
	s_setprio 0
	s_barrier
	s_add_i32 s53, s53, 2
	s_add_u32 s70, s70, 0x100
	s_addc_u32 s71, s71, 0
	s_add_u32 s49, s49, 0x100
	s_addc_u32 s52, s52, 0
	s_cmp_gt_u32 s53, 29
	s_cbranch_scc0 .LBB0_822
	s_and_b64 vcc, exec, s[6:7]
	s_cbranch_vccz .LBB0_825
	s_barrier

; #define PG8_STAGE(bufoff, gbase, voff) do { _Pragma("unroll") for (int _i = 0; _i < 2; ++_i) \
;         __builtin_amdgcn_global_load_lds((const unsigned*)((const char*)(gbase) + (voff)[_i]), (PG8_LAS unsigned*)(lds + (bufoff) + ldsw + _i * 8192), 16, 0, 0); } while (0)
; #define PG8_LDA(dst, b, h) do { _Pragma("unroll") for (int m = 0; m < 4; ++m) _Pragma("unroll") for (int k = 0; k < 2; ++k) dst[m][k] = *(const PG8_LAS bf16x8*)(lds + PG8_SA(b, h) + aoff + m * 2048 + k * 1024); } while (0)
; #define PG8_LDB(dst, b, h) do { _Pragma("unroll") for (int n = 0; n < 2; ++n) _Pragma("unroll") for (int k = 0; k < 2; ++k) dst[n][k] = *(const PG8_LAS bf16x8*)(lds + PG8_SB(b, h) + boff + n * 2048 + k * 1024); } while (0)
; #define PG8_MMA(ai, bj, At, Bt) do { __builtin_amdgcn_s_setprio(1); _Pragma("unroll") for (int m = 0; m < 4; ++m) _Pragma("unroll") for (int n = 0; n < 2; ++n) _Pragma("unroll") for (int k = 0; k < 2; ++k) \
;         acc[ai][bj][m][n] = __builtin_amdgcn_mfma_f32_16x16x32_bf16(Bt[n][k], At[m][k], acc[ai][bj][m][n], 0, 0, 0); __builtin_amdgcn_s_setprio(0); } while (0)
; #define PG8_WAIT_V(n) asm volatile("s_waitcnt vmcnt(" #n ")" ::: "memory")
; #define PG8_WAIT_L(n) asm volatile("s_waitcnt lgkmcnt(" #n ")" ::: "memory")
; template <class Epi, class Sched, bool ALIGN_EPI = false, bool SP2 = false>
; __device__ __forceinline__ void gemm_phase(PG8_LAS unsigned char* lds, const Gemm g, const Sched& S, const Epi& E, const int wid0) {
;     ...
;             const bool last = (t == nt - 2);
;             const char* a1 = cA + (size_t)(t + 1) * kstep;
;             const char* a2 = last ? nA : cA + (size_t)(t + 2) * kstep; const char* b2 = last ? nB : cB + (size_t)(t + 2) * kstep;
;             const char* a3 = a2 + kstep; const char* b3 = b2 + kstep;
;             if (last && has_next) S.a_ready(nxt);
;             if constexpr (SP2) {
;             PG8_LDB(B0, 0, 0); PG8_LDB(B1, 0, 1); PG8_SCHED; PG8_LDA(At, 0, 0); PG8_STAGE(PG8_SA(1, 1), a1 + hstep, voffA);
;             PG8_WAIT_V(8); PG8_WAIT_L(0); PG8_BAR; PG8_MMA(0, 0, At, B0); PG8_MMA(0, 1, At, B1); PG8_BAR; PG8_SCHED;
;             PG8_LDA(At, 0, 1); PG8_STAGE(PG8_SB(0, 0), b2, voffB); PG8_STAGE(PG8_SB(0, 1), b2 + hstep, voffB); PG8_STAGE(PG8_SA(0, 0), a2, voffA);
;             PG8_WAIT_V(8); PG8_WAIT_L(0); PG8_BAR; PG8_MMA(1, 0, At, B0); PG8_MMA(1, 1, At, B1); PG8_BAR; PG8_SCHED;
.LBB0_898:
	s_add_u32 s34, s76, 0xfffe0080
	s_addc_u32 s35, s77, -1
	s_add_i32 s56, 0, 0x10000
	s_cmp_eq_u32 s53, 4
	s_cselect_b32 s79, s3, s35
	s_cselect_b32 s78, s44, s34
	s_cselect_b32 s35, s31, s52
	s_cselect_b32 s34, s48, s49
	s_add_i32 s67, 0, 0x14000
	v_add_u32_e32 v140, s56, v244
	v_add_u32_e32 v156, s67, v244
	ds_read_b128 v[128:131], v140
	ds_read_b128 v[132:135], v140 offset:1024
	ds_read_b128 v[136:139], v140 offset:2048
	ds_read_b128 v[140:143], v140 offset:3072
	ds_read_b128 v[144:147], v156
	ds_read_b128 v[148:151], v156 offset:1024
	ds_read_b128 v[152:155], v156 offset:2048
	ds_read_b128 v[156:159], v156 offset:3072
	v_lshl_add_u64 v[194:195], s[76:77], 0, v[216:217]
	s_add_i32 m0, s37, 0xc000
	ds_read_b128 v[160:163], v248
	ds_read_b128 v[164:167], v248 offset:1024
	ds_read_b128 v[168:171], v248 offset:2048
	ds_read_b128 v[172:175], v248 offset:3072
	ds_read_b128 v[176:179], v248 offset:4096
	ds_read_b128 v[180:183], v248 offset:5120
	ds_read_b128 v[184:187], v248 offset:6144
	ds_read_b128 v[188:191], v248 offset:7168
	global_load_lds_dwordx4 v[194:195], off
	v_lshl_add_u64 v[194:195], s[76:77], 0, v[218:219]
	s_add_i32 m0, s37, 0xe000
	s_nop 0
	global_load_lds_dwordx4 v[194:195], off
	s_waitcnt vmcnt(8)
	s_waitcnt lgkmcnt(0)
	s_barrier
	s_setprio 1
	s_waitcnt lgkmcnt(0)
	v_mfma_f32_16x16x32_bf16 v[124:127], v[128:131], v[160:163], v[124:127]
	v_mfma_f32_16x16x32_bf16 v[120:123], v[136:139], v[160:163], v[120:123]
	v_mfma_f32_16x16x32_bf16 v[108:111], v[128:131], v[168:171], v[108:111]
	v_mfma_f32_16x16x32_bf16 v[104:107], v[136:139], v[168:171], v[104:107]
	v_mfma_f32_16x16x32_bf16 v[92:95], v[128:131], v[176:179], v[92:95]
	v_mfma_f32_16x16x32_bf16 v[88:91], v[136:139], v[176:179], v[88:91]
	v_mfma_f32_16x16x32_bf16 v[76:79], v[128:131], v[184:187], v[76:79]
	v_mfma_f32_16x16x32_bf16 v[72:75], v[136:139], v[184:187], v[72:75]
	v_mfma_f32_16x16x32_bf16 v[124:127], v[132:135], v[164:167], v[124:127]
	v_mfma_f32_16x16x32_bf16 v[120:123], v[140:143], v[164:167], v[120:123]
	v_mfma_f32_16x16x32_bf16 v[108:111], v[132:135], v[172:175], v[108:111]
	v_mfma_f32_16x16x32_bf16 v[104:107], v[140:143], v[172:175], v[104:107]
	v_mfma_f32_16x16x32_bf16 v[92:95], v[132:135], v[180:183], v[92:95]
	v_mfma_f32_16x16x32_bf16 v[88:91], v[140:143], v[180:183], v[88:91]
	v_mfma_f32_16x16x32_bf16 v[76:79], v[132:135], v[188:191], v[76:79]
	v_mfma_f32_16x16x32_bf16 v[72:75], v[140:143], v[188:191], v[72:75]
	v_mfma_f32_16x16x32_bf16 v[116:119], v[144:147], v[160:163], v[116:119]
	v_mfma_f32_16x16x32_bf16 v[112:115], v[152:155], v[160:163], v[112:115]
	v_mfma_f32_16x16x32_bf16 v[100:103], v[144:147], v[168:171], v[100:103]
	v_mfma_f32_16x16x32_bf16 v[96:99], v[152:155], v[168:171], v[96:99]
	v_mfma_f32_16x16x32_bf16 v[84:87], v[144:147], v[176:179], v[84:87]
	v_mfma_f32_16x16x32_bf16 v[80:83], v[152:155], v[176:179], v[80:83]
	v_mfma_f32_16x16x32_bf16 v[68:71], v[144:147], v[184:187], v[68:71]
	v_mfma_f32_16x16x32_bf16 v[64:67], v[152:155], v[184:187], v[64:67]
	v_mfma_f32_16x16x32_bf16 v[116:119], v[148:151], v[164:167], v[116:119]
	v_mfma_f32_16x16x32_bf16 v[112:115], v[156:159], v[164:167], v[112:115]
	v_mfma_f32_16x16x32_bf16 v[100:103], v[148:151], v[172:175], v[100:103]
	v_mfma_f32_16x16x32_bf16 v[96:99], v[156:159], v[172:175], v[96:99]
	v_mfma_f32_16x16x32_bf16 v[84:87], v[148:151], v[180:183], v[84:87]
	v_mfma_f32_16x16x32_bf16 v[80:83], v[156:159], v[180:183], v[80:83]
	v_mfma_f32_16x16x32_bf16 v[68:71], v[148:151], v[188:191], v[68:71]
	v_mfma_f32_16x16x32_bf16 v[64:67], v[156:159], v[188:191], v[64:67]
	s_setprio 0
	s_barrier
	s_add_i32 s56, s56, s23
	v_lshl_add_u64 v[194:195], s[34:35], 0, v[204:205]
	s_mov_b32 m0, s56
	ds_read_b128 v[160:163], v248 offset:16384
	ds_read_b128 v[164:167], v248 offset:17408
	ds_read_b128 v[168:171], v248 offset:18432
	ds_read_b128 v[172:175], v248 offset:19456
	ds_read_b128 v[176:179], v248 offset:20480
	ds_read_b128 v[180:183], v248 offset:21504
	ds_read_b128 v[184:187], v248 offset:22528
	ds_read_b128 v[188:191], v248 offset:23552
	global_load_lds_dwordx4 v[194:195], off
	s_add_i32 m0, s56, 0x2000
	s_add_u32 s56, s34, 0x20000
	v_lshl_add_u64 v[196:197], s[34:35], 0, v[208:209]
	s_addc_u32 s57, s35, 0
	s_add_i32 s67, s67, s23
	global_load_lds_dwordx4 v[196:197], off
	v_lshl_add_u64 v[222:223], s[56:57], 0, v[204:205]
	s_mov_b32 m0, s67
	v_lshl_add_u64 v[224:225], s[78:79], 0, v[206:207]
	global_load_lds_dwordx4 v[222:223], off
	v_lshl_add_u64 v[222:223], s[56:57], 0, v[208:209]
	s_add_i32 m0, s67, 0x2000
	s_nop 0
	global_load_lds_dwordx4 v[222:223], off
	v_lshl_add_u64 v[222:223], s[78:79], 0, v[202:203]
	s_mov_b32 m0, s37
	s_nop 0
	global_load_lds_dwordx4 v[222:223], off
	s_mov_b32 m0, s38
	s_nop 0
	global_load_lds_dwordx4 v[224:225], off
	s_waitcnt vmcnt(8)
	s_waitcnt lgkmcnt(0)
	s_barrier
; #define PG8_STAGE(bufoff, gbase, voff) do { _Pragma("unroll") for (int _i = 0; _i < 2; ++_i) \
;         __builtin_amdgcn_global_load_lds((const unsigned*)((const char*)(gbase) + (voff)[_i]), (PG8_LAS unsigned*)(lds + (bufoff) + ldsw + _i * 8192), 16, 0, 0); } while (0)
; #define PG8_LDA(dst, b, h) do { _Pragma("unroll") for (int m = 0; m < 4; ++m) _Pragma("unroll") for (int k = 0; k < 2; ++k) dst[m][k] = *(const PG8_LAS bf16x8*)(lds + PG8_SA(b, h) + aoff + m * 2048 + k * 1024); } while (0)
; #define PG8_LDB(dst, b, h) do { _Pragma("unroll") for (int n = 0; n < 2; ++n) _Pragma("unroll") for (int k = 0; k < 2; ++k) dst[n][k] = *(const PG8_LAS bf16x8*)(lds + PG8_SB(b, h) + boff + n * 2048 + k * 1024); } while (0)
; #define PG8_MMA(ai, bj, At, Bt) do { __builtin_amdgcn_s_setprio(1); _Pragma("unroll") for (int m = 0; m < 4; ++m) _Pragma("unroll") for (int n = 0; n < 2; ++n) _Pragma("unroll") for (int k = 0; k < 2; ++k) \
;         acc[ai][bj][m][n] = __builtin_amdgcn_mfma_f32_16x16x32_bf16(Bt[n][k], At[m][k], acc[ai][bj][m][n], 0, 0, 0); __builtin_amdgcn_s_setprio(0); } while (0)
; #define PG8_WAIT_V(n) asm volatile("s_waitcnt vmcnt(" #n ")" ::: "memory")
; #define PG8_WAIT_L(n) asm volatile("s_waitcnt lgkmcnt(" #n ")" ::: "memory")
; #define PG8_BAR __builtin_amdgcn_s_barrier()
; #define PG8_SCHED __builtin_amdgcn_sched_barrier(0)
; template <class Epi, class Sched, bool ALIGN_EPI = false, bool SP2 = false>
; __device__ __forceinline__ void gemm_phase(PG8_LAS unsigned char* lds, const Gemm g, const Sched& S, const Epi& E, const int wid0) {
;     ...
;             PG8_WAIT_V(8); PG8_WAIT_L(0); PG8_BAR; PG8_MMA(1, 0, At, B0); PG8_MMA(1, 1, At, B1); PG8_BAR; PG8_SCHED;
;             PG8_LDB(B0, 1, 0); PG8_LDB(B1, 1, 1); PG8_SCHED; PG8_LDA(At, 1, 0); PG8_STAGE(PG8_SA(0, 1), a2 + hstep, voffA);
;             PG8_WAIT_V(8); PG8_WAIT_L(0); PG8_BAR; PG8_MMA(0, 0, At, B0); PG8_MMA(0, 1, At, B1); PG8_BAR; PG8_SCHED;
	s_setprio 1
	s_waitcnt lgkmcnt(0)
	v_mfma_f32_16x16x32_bf16 v[60:63], v[128:131], v[160:163], v[60:63]
	v_mfma_f32_16x16x32_bf16 v[56:59], v[136:139], v[160:163], v[56:59]
	v_mfma_f32_16x16x32_bf16 v[44:47], v[128:131], v[168:171], v[44:47]
	v_mfma_f32_16x16x32_bf16 v[40:43], v[136:139], v[168:171], v[40:43]
	v_mfma_f32_16x16x32_bf16 v[28:31], v[128:131], v[176:179], v[28:31]
	v_mfma_f32_16x16x32_bf16 v[24:27], v[136:139], v[176:179], v[24:27]
	v_mfma_f32_16x16x32_bf16 v[12:15], v[128:131], v[184:187], v[12:15]
	v_mfma_f32_16x16x32_bf16 v[8:11], v[136:139], v[184:187], v[8:11]
	v_mfma_f32_16x16x32_bf16 v[60:63], v[132:135], v[164:167], v[60:63]
	v_mfma_f32_16x16x32_bf16 v[56:59], v[140:143], v[164:167], v[56:59]
	v_mfma_f32_16x16x32_bf16 v[44:47], v[132:135], v[172:175], v[44:47]
	v_mfma_f32_16x16x32_bf16 v[40:43], v[140:143], v[172:175], v[40:43]
	v_mfma_f32_16x16x32_bf16 v[28:31], v[132:135], v[180:183], v[28:31]
	v_mfma_f32_16x16x32_bf16 v[24:27], v[140:143], v[180:183], v[24:27]
	v_mfma_f32_16x16x32_bf16 v[12:15], v[132:135], v[188:191], v[12:15]
	v_mfma_f32_16x16x32_bf16 v[8:11], v[140:143], v[188:191], v[8:11]
	v_mfma_f32_16x16x32_bf16 v[52:55], v[144:147], v[160:163], v[52:55]
	v_mfma_f32_16x16x32_bf16 v[48:51], v[152:155], v[160:163], v[48:51]
	v_mfma_f32_16x16x32_bf16 v[36:39], v[144:147], v[168:171], v[36:39]
	v_mfma_f32_16x16x32_bf16 v[32:35], v[152:155], v[168:171], v[32:35]
	v_mfma_f32_16x16x32_bf16 v[20:23], v[144:147], v[176:179], v[20:23]
	v_mfma_f32_16x16x32_bf16 v[16:19], v[152:155], v[176:179], v[16:19]
	v_mfma_f32_16x16x32_bf16 v[4:7], v[144:147], v[184:187], v[4:7]
	v_mfma_f32_16x16x32_bf16 v[0:3], v[152:155], v[184:187], v[0:3]
	v_mfma_f32_16x16x32_bf16 v[52:55], v[148:151], v[164:167], v[52:55]
	v_mfma_f32_16x16x32_bf16 v[48:51], v[156:159], v[164:167], v[48:51]
	v_mfma_f32_16x16x32_bf16 v[36:39], v[148:151], v[172:175], v[36:39]
	v_mfma_f32_16x16x32_bf16 v[32:35], v[156:159], v[172:175], v[32:35]
	v_mfma_f32_16x16x32_bf16 v[20:23], v[148:151], v[180:183], v[20:23]
	v_mfma_f32_16x16x32_bf16 v[16:19], v[156:159], v[180:183], v[16:19]
	v_mfma_f32_16x16x32_bf16 v[4:7], v[148:151], v[188:191], v[4:7]
	v_mfma_f32_16x16x32_bf16 v[0:3], v[156:159], v[188:191], v[0:3]
	s_setprio 0
	s_barrier
	s_add_i32 s67, 0, 0x18000
	s_add_i32 s83, 0, 0x1c000
	v_add_u32_e32 v140, s67, v244
	v_add_u32_e32 v156, s83, v244
	ds_read_b128 v[128:131], v140
	ds_read_b128 v[132:135], v140 offset:1024
	ds_read_b128 v[136:139], v140 offset:2048
	ds_read_b128 v[140:143], v140 offset:3072
	ds_read_b128 v[144:147], v156
	ds_read_b128 v[148:151], v156 offset:1024
	ds_read_b128 v[152:155], v156 offset:2048
	ds_read_b128 v[156:159], v156 offset:3072
	s_add_u32 s56, s78, 0x20000
	s_addc_u32 s57, s79, 0
	s_mov_b32 m0, s39
	v_lshl_add_u64 v[226:227], s[56:57], 0, v[202:203]
	ds_read_b128 v[160:163], v248 offset:32768
	ds_read_b128 v[164:167], v248 offset:33792
	ds_read_b128 v[168:171], v248 offset:34816
	ds_read_b128 v[172:175], v248 offset:35840
	ds_read_b128 v[176:179], v248 offset:36864
	ds_read_b128 v[180:183], v248 offset:37888
	ds_read_b128 v[184:187], v248 offset:38912
	ds_read_b128 v[188:191], v248 offset:39936
	global_load_lds_dwordx4 v[226:227], off
	v_lshl_add_u64 v[226:227], s[56:57], 0, v[206:207]
	s_mov_b32 m0, s40
	s_nop 0
	global_load_lds_dwordx4 v[226:227], off
	s_waitcnt vmcnt(8)
	s_waitcnt lgkmcnt(0)
	s_barrier
	s_setprio 1
	s_waitcnt lgkmcnt(0)
	v_mfma_f32_16x16x32_bf16 v[124:127], v[128:131], v[160:163], v[124:127]
	v_mfma_f32_16x16x32_bf16 v[120:123], v[136:139], v[160:163], v[120:123]
	v_mfma_f32_16x16x32_bf16 v[108:111], v[128:131], v[168:171], v[108:111]
	v_mfma_f32_16x16x32_bf16 v[104:107], v[136:139], v[168:171], v[104:107]
	v_mfma_f32_16x16x32_bf16 v[92:95], v[128:131], v[176:179], v[92:95]
	v_mfma_f32_16x16x32_bf16 v[88:91], v[136:139], v[176:179], v[88:91]
	v_mfma_f32_16x16x32_bf16 v[76:79], v[128:131], v[184:187], v[76:79]
	v_mfma_f32_16x16x32_bf16 v[72:75], v[136:139], v[184:187], v[72:75]
	v_mfma_f32_16x16x32_bf16 v[124:127], v[132:135], v[164:167], v[124:127]
	v_mfma_f32_16x16x32_bf16 v[120:123], v[140:143], v[164:167], v[120:123]
	v_mfma_f32_16x16x32_bf16 v[108:111], v[132:135], v[172:175], v[108:111]
	v_mfma_f32_16x16x32_bf16 v[104:107], v[140:143], v[172:175], v[104:107]
	v_mfma_f32_16x16x32_bf16 v[92:95], v[132:135], v[180:183], v[92:95]
	v_mfma_f32_16x16x32_bf16 v[88:91], v[140:143], v[180:183], v[88:91]
	v_mfma_f32_16x16x32_bf16 v[76:79], v[132:135], v[188:191], v[76:79]
	v_mfma_f32_16x16x32_bf16 v[72:75], v[140:143], v[188:191], v[72:75]
	v_mfma_f32_16x16x32_bf16 v[116:119], v[144:147], v[160:163], v[116:119]
	v_mfma_f32_16x16x32_bf16 v[112:115], v[152:155], v[160:163], v[112:115]
	v_mfma_f32_16x16x32_bf16 v[100:103], v[144:147], v[168:171], v[100:103]
	v_mfma_f32_16x16x32_bf16 v[96:99], v[152:155], v[168:171], v[96:99]
	v_mfma_f32_16x16x32_bf16 v[84:87], v[144:147], v[176:179], v[84:87]
	v_mfma_f32_16x16x32_bf16 v[80:83], v[152:155], v[176:179], v[80:83]
	v_mfma_f32_16x16x32_bf16 v[68:71], v[144:147], v[184:187], v[68:71]
	v_mfma_f32_16x16x32_bf16 v[64:67], v[152:155], v[184:187], v[64:67]
	v_mfma_f32_16x16x32_bf16 v[116:119], v[148:151], v[164:167], v[116:119]
	v_mfma_f32_16x16x32_bf16 v[112:115], v[156:159], v[164:167], v[112:115]
	v_mfma_f32_16x16x32_bf16 v[100:103], v[148:151], v[172:175], v[100:103]
	v_mfma_f32_16x16x32_bf16 v[96:99], v[156:159], v[172:175], v[96:99]
	v_mfma_f32_16x16x32_bf16 v[84:87], v[148:151], v[180:183], v[84:87]
	v_mfma_f32_16x16x32_bf16 v[80:83], v[156:159], v[180:183], v[80:83]
	v_mfma_f32_16x16x32_bf16 v[68:71], v[148:151], v[188:191], v[68:71]
	v_mfma_f32_16x16x32_bf16 v[64:67], v[156:159], v[188:191], v[64:67]
	s_setprio 0
	s_barrier
; #define PG8_STAGE(bufoff, gbase, voff) do { _Pragma("unroll") for (int _i = 0; _i < 2; ++_i) \
;         __builtin_amdgcn_global_load_lds((const unsigned*)((const char*)(gbase) + (voff)[_i]), (PG8_LAS unsigned*)(lds + (bufoff) + ldsw + _i * 8192), 16, 0, 0); } while (0)
; #define PG8_LDA(dst, b, h) do { _Pragma("unroll") for (int m = 0; m < 4; ++m) _Pragma("unroll") for (int k = 0; k < 2; ++k) dst[m][k] = *(const PG8_LAS bf16x8*)(lds + PG8_SA(b, h) + aoff + m * 2048 + k * 1024); } while (0)
; #define PG8_MMA(ai, bj, At, Bt) do { __builtin_amdgcn_s_setprio(1); _Pragma("unroll") for (int m = 0; m < 4; ++m) _Pragma("unroll") for (int n = 0; n < 2; ++n) _Pragma("unroll") for (int k = 0; k < 2; ++k) \
;         acc[ai][bj][m][n] = __builtin_amdgcn_mfma_f32_16x16x32_bf16(Bt[n][k], At[m][k], acc[ai][bj][m][n], 0, 0, 0); __builtin_amdgcn_s_setprio(0); } while (0)
; #define PG8_WAIT_V(n) asm volatile("s_waitcnt vmcnt(" #n ")" ::: "memory")
; #define PG8_WAIT_L(n) asm volatile("s_waitcnt lgkmcnt(" #n ")" ::: "memory")
; #define PG8_BAR __builtin_amdgcn_s_barrier()
; #define PG8_SCHED __builtin_amdgcn_sched_barrier(0)
; template <class Epi, class Sched, bool ALIGN_EPI = false, bool SP2 = false>
; __device__ __forceinline__ void gemm_phase(PG8_LAS unsigned char* lds, const Gemm g, const Sched& S, const Epi& E, const int wid0) {
;     ...
;             PG8_LDA(At, 1, 1); PG8_STAGE(PG8_SB(1, 0), b3, voffB); PG8_STAGE(PG8_SB(1, 1), b3 + hstep, voffB); PG8_STAGE(PG8_SA(1, 0), a3, voffA);
;             PG8_WAIT_V(8); PG8_WAIT_L(0); PG8_BAR; PG8_MMA(1, 0, At, B0); PG8_MMA(1, 1, At, B1); PG8_BAR; PG8_SCHED;
;     ...
;         if constexpr (ALIGN_EPI) { if (wr == 0) PG8_BAR; }
	s_add_i32 s56, s67, s23
	v_lshl_add_u64 v[194:195], v[194:195], 0, s[54:55]
	s_mov_b32 m0, s56
	ds_read_b128 v[160:163], v248 offset:49152
	ds_read_b128 v[164:167], v248 offset:50176
	ds_read_b128 v[168:171], v248 offset:51200
	ds_read_b128 v[172:175], v248 offset:52224
	ds_read_b128 v[176:179], v248 offset:53248
	ds_read_b128 v[180:183], v248 offset:54272
	ds_read_b128 v[184:187], v248 offset:55296
	ds_read_b128 v[188:191], v248 offset:56320
	global_load_lds_dwordx4 v[194:195], off
	s_add_i32 m0, s56, 0x2000
	s_add_u32 s34, s34, 0x20080
	v_lshl_add_u64 v[194:195], v[196:197], 0, s[54:55]
	s_addc_u32 s35, s35, 0
	s_add_i32 s56, s83, s23
	global_load_lds_dwordx4 v[194:195], off
	v_lshl_add_u64 v[194:195], s[34:35], 0, v[204:205]
	s_mov_b32 m0, s56
	s_nop 0
	global_load_lds_dwordx4 v[194:195], off
	v_lshl_add_u64 v[194:195], s[34:35], 0, v[208:209]
	s_add_i32 m0, s56, 0x2000
	s_nop 0
	global_load_lds_dwordx4 v[194:195], off
	v_lshl_add_u64 v[194:195], v[222:223], 0, s[54:55]
	s_mov_b32 m0, s41
	s_nop 0
	global_load_lds_dwordx4 v[194:195], off
	v_lshl_add_u64 v[194:195], v[224:225], 0, s[54:55]
	s_mov_b32 m0, s47
	s_nop 0
	global_load_lds_dwordx4 v[194:195], off
	s_waitcnt vmcnt(8)
	s_waitcnt lgkmcnt(0)
	s_barrier
	s_setprio 1
	s_waitcnt lgkmcnt(0)
	v_mfma_f32_16x16x32_bf16 v[60:63], v[128:131], v[160:163], v[60:63]
	v_mfma_f32_16x16x32_bf16 v[56:59], v[136:139], v[160:163], v[56:59]
	v_mfma_f32_16x16x32_bf16 v[44:47], v[128:131], v[168:171], v[44:47]
	v_mfma_f32_16x16x32_bf16 v[40:43], v[136:139], v[168:171], v[40:43]
	v_mfma_f32_16x16x32_bf16 v[28:31], v[128:131], v[176:179], v[28:31]
	v_mfma_f32_16x16x32_bf16 v[24:27], v[136:139], v[176:179], v[24:27]
	v_mfma_f32_16x16x32_bf16 v[12:15], v[128:131], v[184:187], v[12:15]
	v_mfma_f32_16x16x32_bf16 v[8:11], v[136:139], v[184:187], v[8:11]
	v_mfma_f32_16x16x32_bf16 v[60:63], v[132:135], v[164:167], v[60:63]
	v_mfma_f32_16x16x32_bf16 v[56:59], v[140:143], v[164:167], v[56:59]
	v_mfma_f32_16x16x32_bf16 v[44:47], v[132:135], v[172:175], v[44:47]
	v_mfma_f32_16x16x32_bf16 v[40:43], v[140:143], v[172:175], v[40:43]
	v_mfma_f32_16x16x32_bf16 v[28:31], v[132:135], v[180:183], v[28:31]
	v_mfma_f32_16x16x32_bf16 v[24:27], v[140:143], v[180:183], v[24:27]
	v_mfma_f32_16x16x32_bf16 v[12:15], v[132:135], v[188:191], v[12:15]
	v_mfma_f32_16x16x32_bf16 v[8:11], v[140:143], v[188:191], v[8:11]
	v_mfma_f32_16x16x32_bf16 v[52:55], v[144:147], v[160:163], v[52:55]
	v_mfma_f32_16x16x32_bf16 v[48:51], v[152:155], v[160:163], v[48:51]
	v_mfma_f32_16x16x32_bf16 v[36:39], v[144:147], v[168:171], v[36:39]
	v_mfma_f32_16x16x32_bf16 v[32:35], v[152:155], v[168:171], v[32:35]
	v_mfma_f32_16x16x32_bf16 v[20:23], v[144:147], v[176:179], v[20:23]
	v_mfma_f32_16x16x32_bf16 v[16:19], v[152:155], v[176:179], v[16:19]
	v_mfma_f32_16x16x32_bf16 v[4:7], v[144:147], v[184:187], v[4:7]
	v_mfma_f32_16x16x32_bf16 v[0:3], v[152:155], v[184:187], v[0:3]
	v_mfma_f32_16x16x32_bf16 v[52:55], v[148:151], v[164:167], v[52:55]
	v_mfma_f32_16x16x32_bf16 v[48:51], v[156:159], v[164:167], v[48:51]
	v_mfma_f32_16x16x32_bf16 v[36:39], v[148:151], v[172:175], v[36:39]
	v_mfma_f32_16x16x32_bf16 v[32:35], v[156:159], v[172:175], v[32:35]
	v_mfma_f32_16x16x32_bf16 v[20:23], v[148:151], v[180:183], v[20:23]
	v_mfma_f32_16x16x32_bf16 v[16:19], v[156:159], v[180:183], v[16:19]
	v_mfma_f32_16x16x32_bf16 v[4:7], v[148:151], v[188:191], v[4:7]
	v_mfma_f32_16x16x32_bf16 v[0:3], v[156:159], v[188:191], v[0:3]
	s_setprio 0
	s_barrier
	s_add_i32 s53, s53, 2
	s_add_u32 s76, s76, 0x100
	s_addc_u32 s77, s77, 0
	s_add_u32 s49, s49, 0x100
	s_addc_u32 s52, s52, 0
	s_cmp_gt_u32 s53, 5
	s_cbranch_scc0 .LBB0_898
	s_and_b64 vcc, exec, s[8:9]
	s_cbranch_vccz .LBB0_901
	s_barrier

; #define PG8_STAGE(bufoff, gbase, voff) do { _Pragma("unroll") for (int _i = 0; _i < 2; ++_i) \
;         __builtin_amdgcn_global_load_lds((const unsigned*)((const char*)(gbase) + (voff)[_i]), (PG8_LAS unsigned*)(lds + (bufoff) + ldsw + _i * 8192), 16, 0, 0); } while (0)
; #define PG8_LDA(dst, b, h) do { _Pragma("unroll") for (int m = 0; m < 4; ++m) _Pragma("unroll") for (int k = 0; k < 2; ++k) dst[m][k] = *(const PG8_LAS bf16x8*)(lds + PG8_SA(b, h) + aoff + m * 2048 + k * 1024); } while (0)
; #define PG8_LDB(dst, b, h) do { _Pragma("unroll") for (int n = 0; n < 2; ++n) _Pragma("unroll") for (int k = 0; k < 2; ++k) dst[n][k] = *(const PG8_LAS bf16x8*)(lds + PG8_SB(b, h) + boff + n * 2048 + k * 1024); } while (0)
; #define PG8_MMA(ai, bj, At, Bt) do { __builtin_amdgcn_s_setprio(1); _Pragma("unroll") for (int m = 0; m < 4; ++m) _Pragma("unroll") for (int n = 0; n < 2; ++n) _Pragma("unroll") for (int k = 0; k < 2; ++k) \
;         acc[ai][bj][m][n] = __builtin_amdgcn_mfma_f32_16x16x32_bf16(Bt[n][k], At[m][k], acc[ai][bj][m][n], 0, 0, 0); __builtin_amdgcn_s_setprio(0); } while (0)
; #define PG8_WAIT_V(n) asm volatile("s_waitcnt vmcnt(" #n ")" ::: "memory")
; #define PG8_WAIT_L(n) asm volatile("s_waitcnt lgkmcnt(" #n ")" ::: "memory")
; template <class Epi, class Sched, bool ALIGN_EPI = false, bool SP2 = false>
; __device__ __forceinline__ void gemm_phase(PG8_LAS unsigned char* lds, const Gemm g, const Sched& S, const Epi& E, const int wid0) {
;     ...
;             const bool last = (t == nt - 2);
;             const char* a1 = cA + (size_t)(t + 1) * kstep;
;             const char* a2 = last ? nA : cA + (size_t)(t + 2) * kstep; const char* b2 = last ? nB : cB + (size_t)(t + 2) * kstep;
;             const char* a3 = a2 + kstep; const char* b3 = b2 + kstep;
;             if (last && has_next) S.a_ready(nxt);
;             if constexpr (SP2) {
;             PG8_LDB(B0, 0, 0); PG8_LDB(B1, 0, 1); PG8_SCHED; PG8_LDA(At, 0, 0); PG8_STAGE(PG8_SA(1, 1), a1 + hstep, voffA);
;             PG8_WAIT_V(8); PG8_WAIT_L(0); PG8_BAR; PG8_MMA(0, 0, At, B0); PG8_MMA(0, 1, At, B1); PG8_BAR; PG8_SCHED;
;             PG8_LDA(At, 0, 1); PG8_STAGE(PG8_SB(0, 0), b2, voffB); PG8_STAGE(PG8_SB(0, 1), b2 + hstep, voffB); PG8_STAGE(PG8_SA(0, 0), a2, voffA);
;             PG8_WAIT_V(8); PG8_WAIT_L(0); PG8_BAR; PG8_MMA(1, 0, At, B0); PG8_MMA(1, 1, At, B1); PG8_BAR; PG8_SCHED;
.LBB0_1148:
	s_add_u32 s34, s36, 0xfffc0080
	s_addc_u32 s35, s37, -1
	s_add_i32 s41, 0, 0x10000
	s_cmp_eq_u32 s40, 12
	s_cselect_b32 s47, s22, s35
	s_cselect_b32 s46, s23, s34
	s_cselect_b32 s35, s11, s39
	s_cselect_b32 s34, s31, s38
	s_add_i32 s44, 0, 0x14000
	v_add_u32_e32 v152, s41, v159
	v_add_u32_e32 v156, s44, v159
	ds_read_b128 v[140:143], v152
	ds_read_b128 v[144:147], v152 offset:1024
	ds_read_b128 v[148:151], v152 offset:2048
	ds_read_b128 v[152:155], v152 offset:3072
	ds_read_b128 v[162:165], v156
	ds_read_b128 v[166:169], v156 offset:1024
	ds_read_b128 v[170:173], v156 offset:2048
	ds_read_b128 v[174:177], v156 offset:3072
	v_lshl_add_u64 v[156:157], s[36:37], 0, v[136:137]
	s_add_i32 m0, s78, 0xc000
	ds_read_b128 v[178:181], v161
	ds_read_b128 v[182:185], v161 offset:1024
	ds_read_b128 v[186:189], v161 offset:2048
	ds_read_b128 v[202:205], v161 offset:3072
	ds_read_b128 v[206:209], v161 offset:4096
	ds_read_b128 v[210:213], v161 offset:5120
	ds_read_b128 v[214:217], v161 offset:6144
	ds_read_b128 v[218:221], v161 offset:7168
	global_load_lds_dwordx4 v[156:157], off
	v_lshl_add_u64 v[156:157], s[36:37], 0, v[138:139]
	s_add_i32 m0, s78, 0xe000
	s_nop 0
	global_load_lds_dwordx4 v[156:157], off
	s_waitcnt vmcnt(8)
	s_waitcnt lgkmcnt(0)
	s_barrier
	s_setprio 1
	s_waitcnt lgkmcnt(0)
	v_mfma_f32_16x16x32_bf16 v[124:127], v[140:143], v[178:181], v[124:127]
	v_mfma_f32_16x16x32_bf16 v[120:123], v[148:151], v[178:181], v[120:123]
	v_mfma_f32_16x16x32_bf16 v[108:111], v[140:143], v[186:189], v[108:111]
	v_mfma_f32_16x16x32_bf16 v[104:107], v[148:151], v[186:189], v[104:107]
	v_mfma_f32_16x16x32_bf16 v[92:95], v[140:143], v[206:209], v[92:95]
	v_mfma_f32_16x16x32_bf16 v[88:91], v[148:151], v[206:209], v[88:91]
	v_mfma_f32_16x16x32_bf16 v[76:79], v[140:143], v[214:217], v[76:79]
	v_mfma_f32_16x16x32_bf16 v[72:75], v[148:151], v[214:217], v[72:75]
	v_mfma_f32_16x16x32_bf16 v[124:127], v[144:147], v[182:185], v[124:127]
	v_mfma_f32_16x16x32_bf16 v[120:123], v[152:155], v[182:185], v[120:123]
	v_mfma_f32_16x16x32_bf16 v[108:111], v[144:147], v[202:205], v[108:111]
	v_mfma_f32_16x16x32_bf16 v[104:107], v[152:155], v[202:205], v[104:107]
	v_mfma_f32_16x16x32_bf16 v[92:95], v[144:147], v[210:213], v[92:95]
	v_mfma_f32_16x16x32_bf16 v[88:91], v[152:155], v[210:213], v[88:91]
	v_mfma_f32_16x16x32_bf16 v[76:79], v[144:147], v[218:221], v[76:79]
	v_mfma_f32_16x16x32_bf16 v[72:75], v[152:155], v[218:221], v[72:75]
	v_mfma_f32_16x16x32_bf16 v[116:119], v[162:165], v[178:181], v[116:119]
	v_mfma_f32_16x16x32_bf16 v[112:115], v[170:173], v[178:181], v[112:115]
	v_mfma_f32_16x16x32_bf16 v[100:103], v[162:165], v[186:189], v[100:103]
	v_mfma_f32_16x16x32_bf16 v[96:99], v[170:173], v[186:189], v[96:99]
	v_mfma_f32_16x16x32_bf16 v[84:87], v[162:165], v[206:209], v[84:87]
	v_mfma_f32_16x16x32_bf16 v[80:83], v[170:173], v[206:209], v[80:83]
	v_mfma_f32_16x16x32_bf16 v[68:71], v[162:165], v[214:217], v[68:71]
	v_mfma_f32_16x16x32_bf16 v[64:67], v[170:173], v[214:217], v[64:67]
	v_mfma_f32_16x16x32_bf16 v[116:119], v[166:169], v[182:185], v[116:119]
	v_mfma_f32_16x16x32_bf16 v[112:115], v[174:177], v[182:185], v[112:115]
	v_mfma_f32_16x16x32_bf16 v[100:103], v[166:169], v[202:205], v[100:103]
	v_mfma_f32_16x16x32_bf16 v[96:99], v[174:177], v[202:205], v[96:99]
	v_mfma_f32_16x16x32_bf16 v[84:87], v[166:169], v[210:213], v[84:87]
	v_mfma_f32_16x16x32_bf16 v[80:83], v[174:177], v[210:213], v[80:83]
	v_mfma_f32_16x16x32_bf16 v[68:71], v[166:169], v[218:221], v[68:71]
	v_mfma_f32_16x16x32_bf16 v[64:67], v[174:177], v[218:221], v[64:67]
	s_setprio 0
	s_barrier
	s_add_i32 s41, s41, s68
	v_lshl_add_u64 v[156:157], s[34:35], 0, v[130:131]
	s_mov_b32 m0, s41
	ds_read_b128 v[178:181], v161 offset:16384
	ds_read_b128 v[182:185], v161 offset:17408
	ds_read_b128 v[186:189], v161 offset:18432
	ds_read_b128 v[202:205], v161 offset:19456
	ds_read_b128 v[206:209], v161 offset:20480
	ds_read_b128 v[210:213], v161 offset:21504
	ds_read_b128 v[214:217], v161 offset:22528
	ds_read_b128 v[218:221], v161 offset:23552
	global_load_lds_dwordx4 v[156:157], off
	s_add_i32 m0, s41, 0x2000
	s_add_u32 s48, s34, 0x40000
	v_lshl_add_u64 v[190:191], s[34:35], 0, v[134:135]
	s_addc_u32 s49, s35, 0
	s_add_i32 s41, s44, s68
	global_load_lds_dwordx4 v[190:191], off
	v_lshl_add_u64 v[194:195], s[48:49], 0, v[130:131]
	s_mov_b32 m0, s41
	v_lshl_add_u64 v[196:197], s[46:47], 0, v[132:133]
	global_load_lds_dwordx4 v[194:195], off
	v_lshl_add_u64 v[194:195], s[48:49], 0, v[134:135]
	s_add_i32 m0, s41, 0x2000
	s_nop 0
	global_load_lds_dwordx4 v[194:195], off
	v_lshl_add_u64 v[194:195], s[46:47], 0, v[128:129]
	s_mov_b32 m0, s78
	s_nop 0
	global_load_lds_dwordx4 v[194:195], off
	s_mov_b32 m0, s79
	s_nop 0
	global_load_lds_dwordx4 v[196:197], off
	s_waitcnt vmcnt(8)
	s_waitcnt lgkmcnt(0)
	s_barrier
; #define PG8_STAGE(bufoff, gbase, voff) do { _Pragma("unroll") for (int _i = 0; _i < 2; ++_i) \
;         __builtin_amdgcn_global_load_lds((const unsigned*)((const char*)(gbase) + (voff)[_i]), (PG8_LAS unsigned*)(lds + (bufoff) + ldsw + _i * 8192), 16, 0, 0); } while (0)
; #define PG8_LDA(dst, b, h) do { _Pragma("unroll") for (int m = 0; m < 4; ++m) _Pragma("unroll") for (int k = 0; k < 2; ++k) dst[m][k] = *(const PG8_LAS bf16x8*)(lds + PG8_SA(b, h) + aoff + m * 2048 + k * 1024); } while (0)
; #define PG8_LDB(dst, b, h) do { _Pragma("unroll") for (int n = 0; n < 2; ++n) _Pragma("unroll") for (int k = 0; k < 2; ++k) dst[n][k] = *(const PG8_LAS bf16x8*)(lds + PG8_SB(b, h) + boff + n * 2048 + k * 1024); } while (0)
; #define PG8_MMA(ai, bj, At, Bt) do { __builtin_amdgcn_s_setprio(1); _Pragma("unroll") for (int m = 0; m < 4; ++m) _Pragma("unroll") for (int n = 0; n < 2; ++n) _Pragma("unroll") for (int k = 0; k < 2; ++k) \
;         acc[ai][bj][m][n] = __builtin_amdgcn_mfma_f32_16x16x32_bf16(Bt[n][k], At[m][k], acc[ai][bj][m][n], 0, 0, 0); __builtin_amdgcn_s_setprio(0); } while (0)
; #define PG8_WAIT_V(n) asm volatile("s_waitcnt vmcnt(" #n ")" ::: "memory")
; #define PG8_WAIT_L(n) asm volatile("s_waitcnt lgkmcnt(" #n ")" ::: "memory")
; #define PG8_BAR __builtin_amdgcn_s_barrier()
; #define PG8_SCHED __builtin_amdgcn_sched_barrier(0)
; template <class Epi, class Sched, bool ALIGN_EPI = false, bool SP2 = false>
; __device__ __forceinline__ void gemm_phase(PG8_LAS unsigned char* lds, const Gemm g, const Sched& S, const Epi& E, const int wid0) {
;     ...
;             PG8_WAIT_V(8); PG8_WAIT_L(0); PG8_BAR; PG8_MMA(1, 0, At, B0); PG8_MMA(1, 1, At, B1); PG8_BAR; PG8_SCHED;
;             PG8_LDB(B0, 1, 0); PG8_LDB(B1, 1, 1); PG8_SCHED; PG8_LDA(At, 1, 0); PG8_STAGE(PG8_SA(0, 1), a2 + hstep, voffA);
;             PG8_WAIT_V(8); PG8_WAIT_L(0); PG8_BAR; PG8_MMA(0, 0, At, B0); PG8_MMA(0, 1, At, B1); PG8_BAR; PG8_SCHED;
	s_setprio 1
	s_waitcnt lgkmcnt(0)
	v_mfma_f32_16x16x32_bf16 v[60:63], v[140:143], v[178:181], v[60:63]
	v_mfma_f32_16x16x32_bf16 v[56:59], v[148:151], v[178:181], v[56:59]
	v_mfma_f32_16x16x32_bf16 v[44:47], v[140:143], v[186:189], v[44:47]
	v_mfma_f32_16x16x32_bf16 v[40:43], v[148:151], v[186:189], v[40:43]
	v_mfma_f32_16x16x32_bf16 v[28:31], v[140:143], v[206:209], v[28:31]
	v_mfma_f32_16x16x32_bf16 v[24:27], v[148:151], v[206:209], v[24:27]
	v_mfma_f32_16x16x32_bf16 v[12:15], v[140:143], v[214:217], v[12:15]
	v_mfma_f32_16x16x32_bf16 v[8:11], v[148:151], v[214:217], v[8:11]
	v_mfma_f32_16x16x32_bf16 v[60:63], v[144:147], v[182:185], v[60:63]
	v_mfma_f32_16x16x32_bf16 v[56:59], v[152:155], v[182:185], v[56:59]
	v_mfma_f32_16x16x32_bf16 v[44:47], v[144:147], v[202:205], v[44:47]
	v_mfma_f32_16x16x32_bf16 v[40:43], v[152:155], v[202:205], v[40:43]
	v_mfma_f32_16x16x32_bf16 v[28:31], v[144:147], v[210:213], v[28:31]
	v_mfma_f32_16x16x32_bf16 v[24:27], v[152:155], v[210:213], v[24:27]
	v_mfma_f32_16x16x32_bf16 v[12:15], v[144:147], v[218:221], v[12:15]
	v_mfma_f32_16x16x32_bf16 v[8:11], v[152:155], v[218:221], v[8:11]
	v_mfma_f32_16x16x32_bf16 v[52:55], v[162:165], v[178:181], v[52:55]
	v_mfma_f32_16x16x32_bf16 v[48:51], v[170:173], v[178:181], v[48:51]
	v_mfma_f32_16x16x32_bf16 v[36:39], v[162:165], v[186:189], v[36:39]
	v_mfma_f32_16x16x32_bf16 v[32:35], v[170:173], v[186:189], v[32:35]
	v_mfma_f32_16x16x32_bf16 v[20:23], v[162:165], v[206:209], v[20:23]
	v_mfma_f32_16x16x32_bf16 v[16:19], v[170:173], v[206:209], v[16:19]
	v_mfma_f32_16x16x32_bf16 v[4:7], v[162:165], v[214:217], v[4:7]
	v_mfma_f32_16x16x32_bf16 v[0:3], v[170:173], v[214:217], v[0:3]
	v_mfma_f32_16x16x32_bf16 v[52:55], v[166:169], v[182:185], v[52:55]
	v_mfma_f32_16x16x32_bf16 v[48:51], v[174:177], v[182:185], v[48:51]
	v_mfma_f32_16x16x32_bf16 v[36:39], v[166:169], v[202:205], v[36:39]
	v_mfma_f32_16x16x32_bf16 v[32:35], v[174:177], v[202:205], v[32:35]
	v_mfma_f32_16x16x32_bf16 v[20:23], v[166:169], v[210:213], v[20:23]
	v_mfma_f32_16x16x32_bf16 v[16:19], v[174:177], v[210:213], v[16:19]
	v_mfma_f32_16x16x32_bf16 v[4:7], v[166:169], v[218:221], v[4:7]
	v_mfma_f32_16x16x32_bf16 v[0:3], v[174:177], v[218:221], v[0:3]
	s_setprio 0
	s_barrier
	s_add_i32 s41, 0, 0x18000
	s_add_i32 s44, 0, 0x1c000
	v_add_u32_e32 v152, s41, v159
	v_add_u32_e32 v174, s44, v159
	ds_read_b128 v[140:143], v152
	ds_read_b128 v[144:147], v152 offset:1024
	ds_read_b128 v[148:151], v152 offset:2048
	ds_read_b128 v[152:155], v152 offset:3072
	ds_read_b128 v[162:165], v174
	ds_read_b128 v[166:169], v174 offset:1024
	ds_read_b128 v[170:173], v174 offset:2048
	ds_read_b128 v[174:177], v174 offset:3072
	s_add_u32 s46, s46, 0x40000
	s_addc_u32 s47, s47, 0
	s_mov_b32 m0, s80
	v_lshl_add_u64 v[222:223], s[46:47], 0, v[128:129]
	ds_read_b128 v[178:181], v161 offset:32768
	ds_read_b128 v[182:185], v161 offset:33792
	ds_read_b128 v[186:189], v161 offset:34816
	ds_read_b128 v[202:205], v161 offset:35840
	ds_read_b128 v[206:209], v161 offset:36864
	ds_read_b128 v[210:213], v161 offset:37888
	ds_read_b128 v[214:217], v161 offset:38912
	ds_read_b128 v[218:221], v161 offset:39936
	global_load_lds_dwordx4 v[222:223], off
	v_lshl_add_u64 v[222:223], s[46:47], 0, v[132:133]
	s_mov_b32 m0, s81
	s_nop 0
	global_load_lds_dwordx4 v[222:223], off
	s_waitcnt vmcnt(8)
	s_waitcnt lgkmcnt(0)
	s_barrier
	s_setprio 1
	s_waitcnt lgkmcnt(0)
	v_mfma_f32_16x16x32_bf16 v[124:127], v[140:143], v[178:181], v[124:127]
	v_mfma_f32_16x16x32_bf16 v[120:123], v[148:151], v[178:181], v[120:123]
	v_mfma_f32_16x16x32_bf16 v[108:111], v[140:143], v[186:189], v[108:111]
	v_mfma_f32_16x16x32_bf16 v[104:107], v[148:151], v[186:189], v[104:107]
	v_mfma_f32_16x16x32_bf16 v[92:95], v[140:143], v[206:209], v[92:95]
	v_mfma_f32_16x16x32_bf16 v[88:91], v[148:151], v[206:209], v[88:91]
	v_mfma_f32_16x16x32_bf16 v[76:79], v[140:143], v[214:217], v[76:79]
	v_mfma_f32_16x16x32_bf16 v[72:75], v[148:151], v[214:217], v[72:75]
	v_mfma_f32_16x16x32_bf16 v[124:127], v[144:147], v[182:185], v[124:127]
	v_mfma_f32_16x16x32_bf16 v[120:123], v[152:155], v[182:185], v[120:123]
	v_mfma_f32_16x16x32_bf16 v[108:111], v[144:147], v[202:205], v[108:111]
	v_mfma_f32_16x16x32_bf16 v[104:107], v[152:155], v[202:205], v[104:107]
	v_mfma_f32_16x16x32_bf16 v[92:95], v[144:147], v[210:213], v[92:95]
	v_mfma_f32_16x16x32_bf16 v[88:91], v[152:155], v[210:213], v[88:91]
	v_mfma_f32_16x16x32_bf16 v[76:79], v[144:147], v[218:221], v[76:79]
	v_mfma_f32_16x16x32_bf16 v[72:75], v[152:155], v[218:221], v[72:75]
	v_mfma_f32_16x16x32_bf16 v[116:119], v[162:165], v[178:181], v[116:119]
	v_mfma_f32_16x16x32_bf16 v[112:115], v[170:173], v[178:181], v[112:115]
	v_mfma_f32_16x16x32_bf16 v[100:103], v[162:165], v[186:189], v[100:103]
	v_mfma_f32_16x16x32_bf16 v[96:99], v[170:173], v[186:189], v[96:99]
	v_mfma_f32_16x16x32_bf16 v[84:87], v[162:165], v[206:209], v[84:87]
	v_mfma_f32_16x16x32_bf16 v[80:83], v[170:173], v[206:209], v[80:83]
	v_mfma_f32_16x16x32_bf16 v[68:71], v[162:165], v[214:217], v[68:71]
	v_mfma_f32_16x16x32_bf16 v[64:67], v[170:173], v[214:217], v[64:67]
	v_mfma_f32_16x16x32_bf16 v[116:119], v[166:169], v[182:185], v[116:119]
	v_mfma_f32_16x16x32_bf16 v[112:115], v[174:177], v[182:185], v[112:115]
	v_mfma_f32_16x16x32_bf16 v[100:103], v[166:169], v[202:205], v[100:103]
	v_mfma_f32_16x16x32_bf16 v[96:99], v[174:177], v[202:205], v[96:99]
	v_mfma_f32_16x16x32_bf16 v[84:87], v[166:169], v[210:213], v[84:87]
	v_mfma_f32_16x16x32_bf16 v[80:83], v[174:177], v[210:213], v[80:83]
	v_mfma_f32_16x16x32_bf16 v[68:71], v[166:169], v[218:221], v[68:71]
	v_mfma_f32_16x16x32_bf16 v[64:67], v[174:177], v[218:221], v[64:67]
	s_setprio 0
	s_barrier
; #define PG8_STAGE(bufoff, gbase, voff) do { _Pragma("unroll") for (int _i = 0; _i < 2; ++_i) \
;         __builtin_amdgcn_global_load_lds((const unsigned*)((const char*)(gbase) + (voff)[_i]), (PG8_LAS unsigned*)(lds + (bufoff) + ldsw + _i * 8192), 16, 0, 0); } while (0)
; #define PG8_LDA(dst, b, h) do { _Pragma("unroll") for (int m = 0; m < 4; ++m) _Pragma("unroll") for (int k = 0; k < 2; ++k) dst[m][k] = *(const PG8_LAS bf16x8*)(lds + PG8_SA(b, h) + aoff + m * 2048 + k * 1024); } while (0)
; #define PG8_MMA(ai, bj, At, Bt) do { __builtin_amdgcn_s_setprio(1); _Pragma("unroll") for (int m = 0; m < 4; ++m) _Pragma("unroll") for (int n = 0; n < 2; ++n) _Pragma("unroll") for (int k = 0; k < 2; ++k) \
;         acc[ai][bj][m][n] = __builtin_amdgcn_mfma_f32_16x16x32_bf16(Bt[n][k], At[m][k], acc[ai][bj][m][n], 0, 0, 0); __builtin_amdgcn_s_setprio(0); } while (0)
; #define PG8_WAIT_V(n) asm volatile("s_waitcnt vmcnt(" #n ")" ::: "memory")
; #define PG8_WAIT_L(n) asm volatile("s_waitcnt lgkmcnt(" #n ")" ::: "memory")
; #define PG8_BAR __builtin_amdgcn_s_barrier()
; #define PG8_SCHED __builtin_amdgcn_sched_barrier(0)
; template <class Epi, class Sched, bool ALIGN_EPI = false, bool SP2 = false>
; __device__ __forceinline__ void gemm_phase(PG8_LAS unsigned char* lds, const Gemm g, const Sched& S, const Epi& E, const int wid0) {
;     ...
;             PG8_LDA(At, 1, 1); PG8_STAGE(PG8_SB(1, 0), b3, voffB); PG8_STAGE(PG8_SB(1, 1), b3 + hstep, voffB); PG8_STAGE(PG8_SA(1, 0), a3, voffA);
;             PG8_WAIT_V(8); PG8_WAIT_L(0); PG8_BAR; PG8_MMA(1, 0, At, B0); PG8_MMA(1, 1, At, B1); PG8_BAR; PG8_SCHED;
;     ...
;         if constexpr (ALIGN_EPI) { if (wr == 0) PG8_BAR; }
	s_add_i32 s41, s41, s68
	v_lshl_add_u64 v[156:157], v[156:157], 0, s[54:55]
	s_mov_b32 m0, s41
	ds_read_b128 v[178:181], v161 offset:49152
	ds_read_b128 v[182:185], v161 offset:50176
	ds_read_b128 v[186:189], v161 offset:51200
	ds_read_b128 v[202:205], v161 offset:52224
	ds_read_b128 v[206:209], v161 offset:53248
	ds_read_b128 v[210:213], v161 offset:54272
	ds_read_b128 v[214:217], v161 offset:55296
	ds_read_b128 v[218:221], v161 offset:56320
	global_load_lds_dwordx4 v[156:157], off
	s_add_i32 m0, s41, 0x2000
	s_add_u32 s34, s34, 0x40080
	v_lshl_add_u64 v[156:157], v[190:191], 0, s[54:55]
	s_addc_u32 s35, s35, 0
	s_add_i32 s41, s44, s68
	global_load_lds_dwordx4 v[156:157], off
	v_lshl_add_u64 v[156:157], s[34:35], 0, v[130:131]
	s_mov_b32 m0, s41
	s_nop 0
	global_load_lds_dwordx4 v[156:157], off
	v_lshl_add_u64 v[156:157], s[34:35], 0, v[134:135]
	s_add_i32 m0, s41, 0x2000
	s_nop 0
	global_load_lds_dwordx4 v[156:157], off
	v_lshl_add_u64 v[156:157], v[194:195], 0, s[54:55]
	s_mov_b32 m0, s82
	s_nop 0
	global_load_lds_dwordx4 v[156:157], off
	v_lshl_add_u64 v[156:157], v[196:197], 0, s[54:55]
	s_mov_b32 m0, s83
	s_nop 0
	global_load_lds_dwordx4 v[156:157], off
	s_waitcnt vmcnt(8)
	s_waitcnt lgkmcnt(0)
	s_barrier
	s_setprio 1
	s_waitcnt lgkmcnt(0)
	v_mfma_f32_16x16x32_bf16 v[60:63], v[140:143], v[178:181], v[60:63]
	v_mfma_f32_16x16x32_bf16 v[56:59], v[148:151], v[178:181], v[56:59]
	v_mfma_f32_16x16x32_bf16 v[44:47], v[140:143], v[186:189], v[44:47]
	v_mfma_f32_16x16x32_bf16 v[40:43], v[148:151], v[186:189], v[40:43]
	v_mfma_f32_16x16x32_bf16 v[28:31], v[140:143], v[206:209], v[28:31]
	v_mfma_f32_16x16x32_bf16 v[24:27], v[148:151], v[206:209], v[24:27]
	v_mfma_f32_16x16x32_bf16 v[12:15], v[140:143], v[214:217], v[12:15]
	v_mfma_f32_16x16x32_bf16 v[8:11], v[148:151], v[214:217], v[8:11]
	v_mfma_f32_16x16x32_bf16 v[60:63], v[144:147], v[182:185], v[60:63]
	v_mfma_f32_16x16x32_bf16 v[56:59], v[152:155], v[182:185], v[56:59]
	v_mfma_f32_16x16x32_bf16 v[44:47], v[144:147], v[202:205], v[44:47]
	v_mfma_f32_16x16x32_bf16 v[40:43], v[152:155], v[202:205], v[40:43]
	v_mfma_f32_16x16x32_bf16 v[28:31], v[144:147], v[210:213], v[28:31]
	v_mfma_f32_16x16x32_bf16 v[24:27], v[152:155], v[210:213], v[24:27]
	v_mfma_f32_16x16x32_bf16 v[12:15], v[144:147], v[218:221], v[12:15]
	v_mfma_f32_16x16x32_bf16 v[8:11], v[152:155], v[218:221], v[8:11]
	v_mfma_f32_16x16x32_bf16 v[52:55], v[162:165], v[178:181], v[52:55]
	v_mfma_f32_16x16x32_bf16 v[48:51], v[170:173], v[178:181], v[48:51]
	v_mfma_f32_16x16x32_bf16 v[36:39], v[162:165], v[186:189], v[36:39]
	v_mfma_f32_16x16x32_bf16 v[32:35], v[170:173], v[186:189], v[32:35]
	v_mfma_f32_16x16x32_bf16 v[20:23], v[162:165], v[206:209], v[20:23]
	v_mfma_f32_16x16x32_bf16 v[16:19], v[170:173], v[206:209], v[16:19]
	v_mfma_f32_16x16x32_bf16 v[4:7], v[162:165], v[214:217], v[4:7]
	v_mfma_f32_16x16x32_bf16 v[0:3], v[170:173], v[214:217], v[0:3]
	v_mfma_f32_16x16x32_bf16 v[52:55], v[166:169], v[182:185], v[52:55]
	v_mfma_f32_16x16x32_bf16 v[48:51], v[174:177], v[182:185], v[48:51]
	v_mfma_f32_16x16x32_bf16 v[36:39], v[166:169], v[202:205], v[36:39]
	v_mfma_f32_16x16x32_bf16 v[32:35], v[174:177], v[202:205], v[32:35]
	v_mfma_f32_16x16x32_bf16 v[20:23], v[166:169], v[210:213], v[20:23]
	v_mfma_f32_16x16x32_bf16 v[16:19], v[174:177], v[210:213], v[16:19]
	v_mfma_f32_16x16x32_bf16 v[4:7], v[166:169], v[218:221], v[4:7]
	v_mfma_f32_16x16x32_bf16 v[0:3], v[174:177], v[218:221], v[0:3]
	s_setprio 0
	s_barrier
	s_add_i32 s40, s40, 2
	s_add_u32 s36, s36, 0x100
	s_addc_u32 s37, s37, 0
	s_add_u32 s38, s38, 0x100
	s_addc_u32 s39, s39, 0
	s_cmp_gt_u32 s40, 13
	s_cbranch_scc0 .LBB0_1148
	s_and_b64 vcc, exec, s[8:9]
	s_cbranch_vccz .LBB0_1151
	s_barrier

; #define PG8_STAGE(bufoff, gbase, voff) do { _Pragma("unroll") for (int _i = 0; _i < 2; ++_i) \
;         __builtin_amdgcn_global_load_lds((const unsigned*)((const char*)(gbase) + (voff)[_i]), (PG8_LAS unsigned*)(lds + (bufoff) + ldsw + _i * 8192), 16, 0, 0); } while (0)
; #define PG8_LDA(dst, b, h) do { _Pragma("unroll") for (int m = 0; m < 4; ++m) _Pragma("unroll") for (int k = 0; k < 2; ++k) dst[m][k] = *(const PG8_LAS bf16x8*)(lds + PG8_SA(b, h) + aoff + m * 2048 + k * 1024); } while (0)
; #define PG8_LDB(dst, b, h) do { _Pragma("unroll") for (int n = 0; n < 2; ++n) _Pragma("unroll") for (int k = 0; k < 2; ++k) dst[n][k] = *(const PG8_LAS bf16x8*)(lds + PG8_SB(b, h) + boff + n * 2048 + k * 1024); } while (0)
; #define PG8_MMA(ai, bj, At, Bt) do { __builtin_amdgcn_s_setprio(1); _Pragma("unroll") for (int m = 0; m < 4; ++m) _Pragma("unroll") for (int n = 0; n < 2; ++n) _Pragma("unroll") for (int k = 0; k < 2; ++k) \
;         acc[ai][bj][m][n] = __builtin_amdgcn_mfma_f32_16x16x32_bf16(Bt[n][k], At[m][k], acc[ai][bj][m][n], 0, 0, 0); __builtin_amdgcn_s_setprio(0); } while (0)
; #define PG8_WAIT_V(n) asm volatile("s_waitcnt vmcnt(" #n ")" ::: "memory")
; #define PG8_WAIT_L(n) asm volatile("s_waitcnt lgkmcnt(" #n ")" ::: "memory")
; template <class Epi, class Sched, bool ALIGN_EPI = false, bool SP2 = false>
; __device__ __forceinline__ void gemm_phase(PG8_LAS unsigned char* lds, const Gemm g, const Sched& S, const Epi& E, const int wid0) {
;     ...
;             const bool last = (t == nt - 2);
;             const char* a1 = cA + (size_t)(t + 1) * kstep;
;             const char* a2 = last ? nA : cA + (size_t)(t + 2) * kstep; const char* b2 = last ? nB : cB + (size_t)(t + 2) * kstep;
;             const char* a3 = a2 + kstep; const char* b3 = b2 + kstep;
;             if (last && has_next) S.a_ready(nxt);
;             if constexpr (SP2) {
;             PG8_LDB(B0, 0, 0); PG8_LDB(B1, 0, 1); PG8_SCHED; PG8_LDA(At, 0, 0); PG8_STAGE(PG8_SA(1, 1), a1 + hstep, voffA);
;             PG8_WAIT_V(8); PG8_WAIT_L(0); PG8_BAR; PG8_MMA(0, 0, At, B0); PG8_MMA(0, 1, At, B1); PG8_BAR; PG8_SCHED;
;             PG8_LDA(At, 0, 1); PG8_STAGE(PG8_SB(0, 0), b2, voffB); PG8_STAGE(PG8_SB(0, 1), b2 + hstep, voffB); PG8_STAGE(PG8_SA(0, 0), a2, voffA);
;             PG8_WAIT_V(8); PG8_WAIT_L(0); PG8_BAR; PG8_MMA(1, 0, At, B0); PG8_MMA(1, 1, At, B1); PG8_BAR; PG8_SCHED;
.LBB0_1172:
	s_add_u32 s34, s36, 0xfff80080
	s_addc_u32 s35, s37, -1
	s_add_i32 s53, 0, 0x10000
	s_cmp_eq_u32 s52, 28
	s_cselect_b32 s47, s40, s35
	s_cselect_b32 s46, s41, s34
	v_add_u32_e32 v144, s53, v147
	s_cselect_b32 s35, s31, s49
	s_cselect_b32 s34, s44, s48
	s_add_i32 s67, 0, 0x14000
	ds_read_b128 v[140:143], v144
	ds_read_b128 v[150:153], v144 offset:1024
	ds_read_b128 v[154:157], v144 offset:2048
	ds_read_b128 v[158:161], v144 offset:3072
	v_add_u32_e32 v144, s67, v147
	ds_read_b128 v[162:165], v144
	ds_read_b128 v[166:169], v144 offset:1024
	ds_read_b128 v[170:173], v144 offset:2048
	ds_read_b128 v[174:177], v144 offset:3072
	v_lshl_add_u64 v[144:145], s[36:37], 0, v[136:137]
	s_add_i32 m0, s7, 0xc000
	ds_read_b128 v[178:181], v149
	ds_read_b128 v[182:185], v149 offset:1024
	ds_read_b128 v[186:189], v149 offset:2048
	ds_read_b128 v[202:205], v149 offset:3072
	ds_read_b128 v[206:209], v149 offset:4096
	ds_read_b128 v[210:213], v149 offset:5120
	ds_read_b128 v[214:217], v149 offset:6144
	ds_read_b128 v[218:221], v149 offset:7168
	global_load_lds_dwordx4 v[144:145], off
	v_lshl_add_u64 v[144:145], s[36:37], 0, v[138:139]
	s_add_i32 m0, s7, 0xe000
	s_nop 0
	global_load_lds_dwordx4 v[144:145], off
	s_waitcnt vmcnt(8)
	s_waitcnt lgkmcnt(0)
	s_barrier
	s_setprio 1
	s_waitcnt lgkmcnt(0)
	v_mfma_f32_16x16x32_bf16 v[124:127], v[140:143], v[178:181], v[124:127]
	v_mfma_f32_16x16x32_bf16 v[120:123], v[154:157], v[178:181], v[120:123]
	v_mfma_f32_16x16x32_bf16 v[108:111], v[140:143], v[186:189], v[108:111]
	v_mfma_f32_16x16x32_bf16 v[104:107], v[154:157], v[186:189], v[104:107]
	v_mfma_f32_16x16x32_bf16 v[92:95], v[140:143], v[206:209], v[92:95]
	v_mfma_f32_16x16x32_bf16 v[88:91], v[154:157], v[206:209], v[88:91]
	v_mfma_f32_16x16x32_bf16 v[76:79], v[140:143], v[214:217], v[76:79]
	v_mfma_f32_16x16x32_bf16 v[72:75], v[154:157], v[214:217], v[72:75]
	v_mfma_f32_16x16x32_bf16 v[124:127], v[150:153], v[182:185], v[124:127]
	v_mfma_f32_16x16x32_bf16 v[120:123], v[158:161], v[182:185], v[120:123]
	v_mfma_f32_16x16x32_bf16 v[108:111], v[150:153], v[202:205], v[108:111]
	v_mfma_f32_16x16x32_bf16 v[104:107], v[158:161], v[202:205], v[104:107]
	v_mfma_f32_16x16x32_bf16 v[92:95], v[150:153], v[210:213], v[92:95]
	v_mfma_f32_16x16x32_bf16 v[88:91], v[158:161], v[210:213], v[88:91]
	v_mfma_f32_16x16x32_bf16 v[76:79], v[150:153], v[218:221], v[76:79]
	v_mfma_f32_16x16x32_bf16 v[72:75], v[158:161], v[218:221], v[72:75]
	v_mfma_f32_16x16x32_bf16 v[116:119], v[162:165], v[178:181], v[116:119]
	v_mfma_f32_16x16x32_bf16 v[112:115], v[170:173], v[178:181], v[112:115]
	v_mfma_f32_16x16x32_bf16 v[100:103], v[162:165], v[186:189], v[100:103]
	v_mfma_f32_16x16x32_bf16 v[96:99], v[170:173], v[186:189], v[96:99]
	v_mfma_f32_16x16x32_bf16 v[84:87], v[162:165], v[206:209], v[84:87]
	v_mfma_f32_16x16x32_bf16 v[80:83], v[170:173], v[206:209], v[80:83]
	v_mfma_f32_16x16x32_bf16 v[68:71], v[162:165], v[214:217], v[68:71]
	v_mfma_f32_16x16x32_bf16 v[64:67], v[170:173], v[214:217], v[64:67]
	v_mfma_f32_16x16x32_bf16 v[116:119], v[166:169], v[182:185], v[116:119]
	v_mfma_f32_16x16x32_bf16 v[112:115], v[174:177], v[182:185], v[112:115]
	v_mfma_f32_16x16x32_bf16 v[100:103], v[166:169], v[202:205], v[100:103]
	v_mfma_f32_16x16x32_bf16 v[96:99], v[174:177], v[202:205], v[96:99]
	v_mfma_f32_16x16x32_bf16 v[84:87], v[166:169], v[210:213], v[84:87]
	v_mfma_f32_16x16x32_bf16 v[80:83], v[174:177], v[210:213], v[80:83]
	v_mfma_f32_16x16x32_bf16 v[68:71], v[166:169], v[218:221], v[68:71]
	v_mfma_f32_16x16x32_bf16 v[64:67], v[174:177], v[218:221], v[64:67]
	s_setprio 0
	s_barrier
	s_add_i32 s53, s53, s6
	v_lshl_add_u64 v[144:145], s[34:35], 0, v[132:133]
	s_mov_b32 m0, s53
	ds_read_b128 v[178:181], v149 offset:16384
	ds_read_b128 v[182:185], v149 offset:17408
	ds_read_b128 v[186:189], v149 offset:18432
	ds_read_b128 v[202:205], v149 offset:19456
	ds_read_b128 v[206:209], v149 offset:20480
	ds_read_b128 v[210:213], v149 offset:21504
	ds_read_b128 v[214:217], v149 offset:22528
	ds_read_b128 v[218:221], v149 offset:23552
	global_load_lds_dwordx4 v[144:145], off
	s_add_i32 m0, s53, 0x2000
	s_add_u32 s56, s34, 0x80000
	v_lshl_add_u64 v[190:191], s[34:35], 0, v[128:129]
	s_addc_u32 s57, s35, 0
	s_add_i32 s53, s67, s6
	global_load_lds_dwordx4 v[190:191], off
	v_lshl_add_u64 v[194:195], s[56:57], 0, v[132:133]
	s_mov_b32 m0, s53
	v_lshl_add_u64 v[196:197], s[46:47], 0, v[130:131]
	global_load_lds_dwordx4 v[194:195], off
	v_lshl_add_u64 v[194:195], s[56:57], 0, v[128:129]
	s_add_i32 m0, s53, 0x2000
	s_nop 0
	global_load_lds_dwordx4 v[194:195], off
	v_lshl_add_u64 v[194:195], s[46:47], 0, v[134:135]
	s_mov_b32 m0, s7
	s_nop 0
	global_load_lds_dwordx4 v[194:195], off
	s_mov_b32 m0, s22
	s_nop 0
	global_load_lds_dwordx4 v[196:197], off
	s_waitcnt vmcnt(8)
	s_waitcnt lgkmcnt(0)
	s_barrier
; #define PG8_STAGE(bufoff, gbase, voff) do { _Pragma("unroll") for (int _i = 0; _i < 2; ++_i) \
;         __builtin_amdgcn_global_load_lds((const unsigned*)((const char*)(gbase) + (voff)[_i]), (PG8_LAS unsigned*)(lds + (bufoff) + ldsw + _i * 8192), 16, 0, 0); } while (0)
; #define PG8_LDA(dst, b, h) do { _Pragma("unroll") for (int m = 0; m < 4; ++m) _Pragma("unroll") for (int k = 0; k < 2; ++k) dst[m][k] = *(const PG8_LAS bf16x8*)(lds + PG8_SA(b, h) + aoff + m * 2048 + k * 1024); } while (0)
; #define PG8_LDB(dst, b, h) do { _Pragma("unroll") for (int n = 0; n < 2; ++n) _Pragma("unroll") for (int k = 0; k < 2; ++k) dst[n][k] = *(const PG8_LAS bf16x8*)(lds + PG8_SB(b, h) + boff + n * 2048 + k * 1024); } while (0)
; #define PG8_MMA(ai, bj, At, Bt) do { __builtin_amdgcn_s_setprio(1); _Pragma("unroll") for (int m = 0; m < 4; ++m) _Pragma("unroll") for (int n = 0; n < 2; ++n) _Pragma("unroll") for (int k = 0; k < 2; ++k) \
;         acc[ai][bj][m][n] = __builtin_amdgcn_mfma_f32_16x16x32_bf16(Bt[n][k], At[m][k], acc[ai][bj][m][n], 0, 0, 0); __builtin_amdgcn_s_setprio(0); } while (0)
; #define PG8_WAIT_V(n) asm volatile("s_waitcnt vmcnt(" #n ")" ::: "memory")
; #define PG8_WAIT_L(n) asm volatile("s_waitcnt lgkmcnt(" #n ")" ::: "memory")
; #define PG8_BAR __builtin_amdgcn_s_barrier()
; #define PG8_SCHED __builtin_amdgcn_sched_barrier(0)
; template <class Epi, class Sched, bool ALIGN_EPI = false, bool SP2 = false>
; __device__ __forceinline__ void gemm_phase(PG8_LAS unsigned char* lds, const Gemm g, const Sched& S, const Epi& E, const int wid0) {
;     ...
;             PG8_WAIT_V(8); PG8_WAIT_L(0); PG8_BAR; PG8_MMA(1, 0, At, B0); PG8_MMA(1, 1, At, B1); PG8_BAR; PG8_SCHED;
;             PG8_LDB(B0, 1, 0); PG8_LDB(B1, 1, 1); PG8_SCHED; PG8_LDA(At, 1, 0); PG8_STAGE(PG8_SA(0, 1), a2 + hstep, voffA);
;             PG8_WAIT_V(8); PG8_WAIT_L(0); PG8_BAR; PG8_MMA(0, 0, At, B0); PG8_MMA(0, 1, At, B1); PG8_BAR; PG8_SCHED;
	s_setprio 1
	s_waitcnt lgkmcnt(0)
	v_mfma_f32_16x16x32_bf16 v[60:63], v[140:143], v[178:181], v[60:63]
	v_mfma_f32_16x16x32_bf16 v[56:59], v[154:157], v[178:181], v[56:59]
	v_mfma_f32_16x16x32_bf16 v[44:47], v[140:143], v[186:189], v[44:47]
	v_mfma_f32_16x16x32_bf16 v[40:43], v[154:157], v[186:189], v[40:43]
	v_mfma_f32_16x16x32_bf16 v[28:31], v[140:143], v[206:209], v[28:31]
	v_mfma_f32_16x16x32_bf16 v[24:27], v[154:157], v[206:209], v[24:27]
	v_mfma_f32_16x16x32_bf16 v[12:15], v[140:143], v[214:217], v[12:15]
	v_mfma_f32_16x16x32_bf16 v[8:11], v[154:157], v[214:217], v[8:11]
	v_mfma_f32_16x16x32_bf16 v[60:63], v[150:153], v[182:185], v[60:63]
	v_mfma_f32_16x16x32_bf16 v[56:59], v[158:161], v[182:185], v[56:59]
	v_mfma_f32_16x16x32_bf16 v[44:47], v[150:153], v[202:205], v[44:47]
	v_mfma_f32_16x16x32_bf16 v[40:43], v[158:161], v[202:205], v[40:43]
	v_mfma_f32_16x16x32_bf16 v[28:31], v[150:153], v[210:213], v[28:31]
	v_mfma_f32_16x16x32_bf16 v[24:27], v[158:161], v[210:213], v[24:27]
	v_mfma_f32_16x16x32_bf16 v[12:15], v[150:153], v[218:221], v[12:15]
	v_mfma_f32_16x16x32_bf16 v[8:11], v[158:161], v[218:221], v[8:11]
	v_mfma_f32_16x16x32_bf16 v[52:55], v[162:165], v[178:181], v[52:55]
	v_mfma_f32_16x16x32_bf16 v[48:51], v[170:173], v[178:181], v[48:51]
	v_mfma_f32_16x16x32_bf16 v[36:39], v[162:165], v[186:189], v[36:39]
	v_mfma_f32_16x16x32_bf16 v[32:35], v[170:173], v[186:189], v[32:35]
	v_mfma_f32_16x16x32_bf16 v[20:23], v[162:165], v[206:209], v[20:23]
	v_mfma_f32_16x16x32_bf16 v[16:19], v[170:173], v[206:209], v[16:19]
	v_mfma_f32_16x16x32_bf16 v[4:7], v[162:165], v[214:217], v[4:7]
	v_mfma_f32_16x16x32_bf16 v[0:3], v[170:173], v[214:217], v[0:3]
	v_mfma_f32_16x16x32_bf16 v[52:55], v[166:169], v[182:185], v[52:55]
	v_mfma_f32_16x16x32_bf16 v[48:51], v[174:177], v[182:185], v[48:51]
	v_mfma_f32_16x16x32_bf16 v[36:39], v[166:169], v[202:205], v[36:39]
	v_mfma_f32_16x16x32_bf16 v[32:35], v[174:177], v[202:205], v[32:35]
	v_mfma_f32_16x16x32_bf16 v[20:23], v[166:169], v[210:213], v[20:23]
	v_mfma_f32_16x16x32_bf16 v[16:19], v[174:177], v[210:213], v[16:19]
	v_mfma_f32_16x16x32_bf16 v[4:7], v[166:169], v[218:221], v[4:7]
	v_mfma_f32_16x16x32_bf16 v[0:3], v[174:177], v[218:221], v[0:3]
	s_setprio 0
	s_barrier
	s_add_i32 s53, 0, 0x18000
	s_add_i32 s56, 0, 0x1c000
	v_add_u32_e32 v158, s53, v147
	v_add_u32_e32 v174, s56, v147
	ds_read_b128 v[140:143], v158
	ds_read_b128 v[150:153], v158 offset:1024
	ds_read_b128 v[154:157], v158 offset:2048
	ds_read_b128 v[158:161], v158 offset:3072
	ds_read_b128 v[162:165], v174
	ds_read_b128 v[166:169], v174 offset:1024
	ds_read_b128 v[170:173], v174 offset:2048
	ds_read_b128 v[174:177], v174 offset:3072
	s_add_u32 s46, s46, 0x80000
	s_addc_u32 s47, s47, 0
	s_mov_b32 m0, s23
	v_lshl_add_u64 v[222:223], s[46:47], 0, v[134:135]
	ds_read_b128 v[178:181], v149 offset:32768
	ds_read_b128 v[182:185], v149 offset:33792
	ds_read_b128 v[186:189], v149 offset:34816
	ds_read_b128 v[202:205], v149 offset:35840
	ds_read_b128 v[206:209], v149 offset:36864
	ds_read_b128 v[210:213], v149 offset:37888
	ds_read_b128 v[214:217], v149 offset:38912
	ds_read_b128 v[218:221], v149 offset:39936
	global_load_lds_dwordx4 v[222:223], off
	v_lshl_add_u64 v[222:223], s[46:47], 0, v[130:131]
	s_mov_b32 m0, s38
	s_nop 0
	global_load_lds_dwordx4 v[222:223], off
	s_waitcnt vmcnt(8)
	s_waitcnt lgkmcnt(0)
	s_barrier
	s_setprio 1
	s_waitcnt lgkmcnt(0)
	v_mfma_f32_16x16x32_bf16 v[124:127], v[140:143], v[178:181], v[124:127]
	v_mfma_f32_16x16x32_bf16 v[120:123], v[154:157], v[178:181], v[120:123]
	v_mfma_f32_16x16x32_bf16 v[108:111], v[140:143], v[186:189], v[108:111]
	v_mfma_f32_16x16x32_bf16 v[104:107], v[154:157], v[186:189], v[104:107]
	v_mfma_f32_16x16x32_bf16 v[92:95], v[140:143], v[206:209], v[92:95]
	v_mfma_f32_16x16x32_bf16 v[88:91], v[154:157], v[206:209], v[88:91]
	v_mfma_f32_16x16x32_bf16 v[76:79], v[140:143], v[214:217], v[76:79]
	v_mfma_f32_16x16x32_bf16 v[72:75], v[154:157], v[214:217], v[72:75]
	v_mfma_f32_16x16x32_bf16 v[124:127], v[150:153], v[182:185], v[124:127]
	v_mfma_f32_16x16x32_bf16 v[120:123], v[158:161], v[182:185], v[120:123]
	v_mfma_f32_16x16x32_bf16 v[108:111], v[150:153], v[202:205], v[108:111]
	v_mfma_f32_16x16x32_bf16 v[104:107], v[158:161], v[202:205], v[104:107]
	v_mfma_f32_16x16x32_bf16 v[92:95], v[150:153], v[210:213], v[92:95]
	v_mfma_f32_16x16x32_bf16 v[88:91], v[158:161], v[210:213], v[88:91]
	v_mfma_f32_16x16x32_bf16 v[76:79], v[150:153], v[218:221], v[76:79]
	v_mfma_f32_16x16x32_bf16 v[72:75], v[158:161], v[218:221], v[72:75]
	v_mfma_f32_16x16x32_bf16 v[116:119], v[162:165], v[178:181], v[116:119]
	v_mfma_f32_16x16x32_bf16 v[112:115], v[170:173], v[178:181], v[112:115]
	v_mfma_f32_16x16x32_bf16 v[100:103], v[162:165], v[186:189], v[100:103]
	v_mfma_f32_16x16x32_bf16 v[96:99], v[170:173], v[186:189], v[96:99]
	v_mfma_f32_16x16x32_bf16 v[84:87], v[162:165], v[206:209], v[84:87]
	v_mfma_f32_16x16x32_bf16 v[80:83], v[170:173], v[206:209], v[80:83]
	v_mfma_f32_16x16x32_bf16 v[68:71], v[162:165], v[214:217], v[68:71]
	v_mfma_f32_16x16x32_bf16 v[64:67], v[170:173], v[214:217], v[64:67]
	v_mfma_f32_16x16x32_bf16 v[116:119], v[166:169], v[182:185], v[116:119]
	v_mfma_f32_16x16x32_bf16 v[112:115], v[174:177], v[182:185], v[112:115]
	v_mfma_f32_16x16x32_bf16 v[100:103], v[166:169], v[202:205], v[100:103]
	v_mfma_f32_16x16x32_bf16 v[96:99], v[174:177], v[202:205], v[96:99]
	v_mfma_f32_16x16x32_bf16 v[84:87], v[166:169], v[210:213], v[84:87]
	v_mfma_f32_16x16x32_bf16 v[80:83], v[174:177], v[210:213], v[80:83]
	v_mfma_f32_16x16x32_bf16 v[68:71], v[166:169], v[218:221], v[68:71]
	v_mfma_f32_16x16x32_bf16 v[64:67], v[174:177], v[218:221], v[64:67]
	s_setprio 0
	s_barrier
; #define PG8_STAGE(bufoff, gbase, voff) do { _Pragma("unroll") for (int _i = 0; _i < 2; ++_i) \
;         __builtin_amdgcn_global_load_lds((const unsigned*)((const char*)(gbase) + (voff)[_i]), (PG8_LAS unsigned*)(lds + (bufoff) + ldsw + _i * 8192), 16, 0, 0); } while (0)
; #define PG8_LDA(dst, b, h) do { _Pragma("unroll") for (int m = 0; m < 4; ++m) _Pragma("unroll") for (int k = 0; k < 2; ++k) dst[m][k] = *(const PG8_LAS bf16x8*)(lds + PG8_SA(b, h) + aoff + m * 2048 + k * 1024); } while (0)
; #define PG8_MMA(ai, bj, At, Bt) do { __builtin_amdgcn_s_setprio(1); _Pragma("unroll") for (int m = 0; m < 4; ++m) _Pragma("unroll") for (int n = 0; n < 2; ++n) _Pragma("unroll") for (int k = 0; k < 2; ++k) \
;         acc[ai][bj][m][n] = __builtin_amdgcn_mfma_f32_16x16x32_bf16(Bt[n][k], At[m][k], acc[ai][bj][m][n], 0, 0, 0); __builtin_amdgcn_s_setprio(0); } while (0)
; #define PG8_WAIT_V(n) asm volatile("s_waitcnt vmcnt(" #n ")" ::: "memory")
; #define PG8_WAIT_L(n) asm volatile("s_waitcnt lgkmcnt(" #n ")" ::: "memory")
; #define PG8_BAR __builtin_amdgcn_s_barrier()
; #define PG8_SCHED __builtin_amdgcn_sched_barrier(0)
; template <class Epi, class Sched, bool ALIGN_EPI = false, bool SP2 = false>
; __device__ __forceinline__ void gemm_phase(PG8_LAS unsigned char* lds, const Gemm g, const Sched& S, const Epi& E, const int wid0) {
;     ...
;             PG8_LDA(At, 1, 1); PG8_STAGE(PG8_SB(1, 0), b3, voffB); PG8_STAGE(PG8_SB(1, 1), b3 + hstep, voffB); PG8_STAGE(PG8_SA(1, 0), a3, voffA);
;             PG8_WAIT_V(8); PG8_WAIT_L(0); PG8_BAR; PG8_MMA(1, 0, At, B0); PG8_MMA(1, 1, At, B1); PG8_BAR; PG8_SCHED;
;     ...
;         if constexpr (ALIGN_EPI) { if (wr == 0) PG8_BAR; }
	s_add_i32 s46, s53, s6
	v_lshl_add_u64 v[144:145], v[144:145], 0, s[54:55]
	s_mov_b32 m0, s46
	ds_read_b128 v[178:181], v149 offset:49152
	ds_read_b128 v[182:185], v149 offset:50176
	ds_read_b128 v[186:189], v149 offset:51200
	ds_read_b128 v[202:205], v149 offset:52224
	ds_read_b128 v[206:209], v149 offset:53248
	ds_read_b128 v[210:213], v149 offset:54272
	ds_read_b128 v[214:217], v149 offset:55296
	ds_read_b128 v[218:221], v149 offset:56320
	global_load_lds_dwordx4 v[144:145], off
	s_add_i32 m0, s46, 0x2000
	s_add_u32 s34, s34, 0x80080
	v_lshl_add_u64 v[144:145], v[190:191], 0, s[54:55]
	s_addc_u32 s35, s35, 0
	s_add_i32 s46, s56, s6
	global_load_lds_dwordx4 v[144:145], off
	v_lshl_add_u64 v[144:145], s[34:35], 0, v[132:133]
	s_mov_b32 m0, s46
	s_nop 0
	global_load_lds_dwordx4 v[144:145], off
	v_lshl_add_u64 v[144:145], s[34:35], 0, v[128:129]
	s_add_i32 m0, s46, 0x2000
	s_nop 0
	global_load_lds_dwordx4 v[144:145], off
	v_lshl_add_u64 v[144:145], v[194:195], 0, s[54:55]
	s_mov_b32 m0, s39
	s_nop 0
	global_load_lds_dwordx4 v[144:145], off
	v_lshl_add_u64 v[144:145], v[196:197], 0, s[54:55]
	s_mov_b32 m0, s68
	s_nop 0
	global_load_lds_dwordx4 v[144:145], off
	s_waitcnt vmcnt(8)
	s_waitcnt lgkmcnt(0)
	s_barrier
	s_setprio 1
	s_waitcnt lgkmcnt(0)
	v_mfma_f32_16x16x32_bf16 v[60:63], v[140:143], v[178:181], v[60:63]
	v_mfma_f32_16x16x32_bf16 v[56:59], v[154:157], v[178:181], v[56:59]
	v_mfma_f32_16x16x32_bf16 v[44:47], v[140:143], v[186:189], v[44:47]
	v_mfma_f32_16x16x32_bf16 v[40:43], v[154:157], v[186:189], v[40:43]
	v_mfma_f32_16x16x32_bf16 v[28:31], v[140:143], v[206:209], v[28:31]
	v_mfma_f32_16x16x32_bf16 v[24:27], v[154:157], v[206:209], v[24:27]
	v_mfma_f32_16x16x32_bf16 v[12:15], v[140:143], v[214:217], v[12:15]
	v_mfma_f32_16x16x32_bf16 v[8:11], v[154:157], v[214:217], v[8:11]
	v_mfma_f32_16x16x32_bf16 v[60:63], v[150:153], v[182:185], v[60:63]
	v_mfma_f32_16x16x32_bf16 v[56:59], v[158:161], v[182:185], v[56:59]
	v_mfma_f32_16x16x32_bf16 v[44:47], v[150:153], v[202:205], v[44:47]
	v_mfma_f32_16x16x32_bf16 v[40:43], v[158:161], v[202:205], v[40:43]
	v_mfma_f32_16x16x32_bf16 v[28:31], v[150:153], v[210:213], v[28:31]
	v_mfma_f32_16x16x32_bf16 v[24:27], v[158:161], v[210:213], v[24:27]
	v_mfma_f32_16x16x32_bf16 v[12:15], v[150:153], v[218:221], v[12:15]
	v_mfma_f32_16x16x32_bf16 v[8:11], v[158:161], v[218:221], v[8:11]
	v_mfma_f32_16x16x32_bf16 v[52:55], v[162:165], v[178:181], v[52:55]
	v_mfma_f32_16x16x32_bf16 v[48:51], v[170:173], v[178:181], v[48:51]
	v_mfma_f32_16x16x32_bf16 v[36:39], v[162:165], v[186:189], v[36:39]
	v_mfma_f32_16x16x32_bf16 v[32:35], v[170:173], v[186:189], v[32:35]
	v_mfma_f32_16x16x32_bf16 v[20:23], v[162:165], v[206:209], v[20:23]
	v_mfma_f32_16x16x32_bf16 v[16:19], v[170:173], v[206:209], v[16:19]
	v_mfma_f32_16x16x32_bf16 v[4:7], v[162:165], v[214:217], v[4:7]
	v_mfma_f32_16x16x32_bf16 v[0:3], v[170:173], v[214:217], v[0:3]
	v_mfma_f32_16x16x32_bf16 v[52:55], v[166:169], v[182:185], v[52:55]
	v_mfma_f32_16x16x32_bf16 v[48:51], v[174:177], v[182:185], v[48:51]
	v_mfma_f32_16x16x32_bf16 v[36:39], v[166:169], v[202:205], v[36:39]
	v_mfma_f32_16x16x32_bf16 v[32:35], v[174:177], v[202:205], v[32:35]
	v_mfma_f32_16x16x32_bf16 v[20:23], v[166:169], v[210:213], v[20:23]
	v_mfma_f32_16x16x32_bf16 v[16:19], v[174:177], v[210:213], v[16:19]
	v_mfma_f32_16x16x32_bf16 v[4:7], v[166:169], v[218:221], v[4:7]
	v_mfma_f32_16x16x32_bf16 v[0:3], v[174:177], v[218:221], v[0:3]
	s_setprio 0
	s_barrier
	s_add_i32 s52, s52, 2
	s_add_u32 s36, s36, 0x100
	s_addc_u32 s37, s37, 0
	s_add_u32 s48, s48, 0x100
	s_addc_u32 s49, s49, 0
	s_cmp_gt_u32 s52, 29
	s_cbranch_scc0 .LBB0_1172
	s_and_b64 vcc, exec, s[10:11]
	s_cbranch_vccz .LBB0_1175
	s_barrier

; #define PG8_STAGE(bufoff, gbase, voff) do { _Pragma("unroll") for (int _i = 0; _i < 2; ++_i) \
;         __builtin_amdgcn_global_load_lds((const unsigned*)((const char*)(gbase) + (voff)[_i]), (PG8_LAS unsigned*)(lds + (bufoff) + ldsw + _i * 8192), 16, 0, 0); } while (0)
; #define PG8_LDA(dst, b, h) do { _Pragma("unroll") for (int m = 0; m < 4; ++m) _Pragma("unroll") for (int k = 0; k < 2; ++k) dst[m][k] = *(const PG8_LAS bf16x8*)(lds + PG8_SA(b, h) + aoff + m * 2048 + k * 1024); } while (0)
; #define PG8_LDB(dst, b, h) do { _Pragma("unroll") for (int n = 0; n < 2; ++n) _Pragma("unroll") for (int k = 0; k < 2; ++k) dst[n][k] = *(const PG8_LAS bf16x8*)(lds + PG8_SB(b, h) + boff + n * 2048 + k * 1024); } while (0)
; #define PG8_MMA(ai, bj, At, Bt) do { __builtin_amdgcn_s_setprio(1); _Pragma("unroll") for (int m = 0; m < 4; ++m) _Pragma("unroll") for (int n = 0; n < 2; ++n) _Pragma("unroll") for (int k = 0; k < 2; ++k) \
;         acc[ai][bj][m][n] = __builtin_amdgcn_mfma_f32_16x16x32_bf16(Bt[n][k], At[m][k], acc[ai][bj][m][n], 0, 0, 0); __builtin_amdgcn_s_setprio(0); } while (0)
; #define PG8_WAIT_V(n) asm volatile("s_waitcnt vmcnt(" #n ")" ::: "memory")
; #define PG8_WAIT_L(n) asm volatile("s_waitcnt lgkmcnt(" #n ")" ::: "memory")
; template <class Epi, class Sched, bool ALIGN_EPI = false, bool SP2 = false>
; __device__ __forceinline__ void gemm_phase(PG8_LAS unsigned char* lds, const Gemm g, const Sched& S, const Epi& E, const int wid0) {
;     ...
;             const bool last = (t == nt - 2);
;             const char* a1 = cA + (size_t)(t + 1) * kstep;
;             const char* a2 = last ? nA : cA + (size_t)(t + 2) * kstep; const char* b2 = last ? nB : cB + (size_t)(t + 2) * kstep;
;             const char* a3 = a2 + kstep; const char* b3 = b2 + kstep;
;             if (last && has_next) S.a_ready(nxt);
;             if constexpr (SP2) {
;             PG8_LDB(B0, 0, 0); PG8_LDB(B1, 0, 1); PG8_SCHED; PG8_LDA(At, 0, 0); PG8_STAGE(PG8_SA(1, 1), a1 + hstep, voffA);
;             PG8_WAIT_V(8); PG8_WAIT_L(0); PG8_BAR; PG8_MMA(0, 0, At, B0); PG8_MMA(0, 1, At, B1); PG8_BAR; PG8_SCHED;
;             PG8_LDA(At, 0, 1); PG8_STAGE(PG8_SB(0, 0), b2, voffB); PG8_STAGE(PG8_SB(0, 1), b2 + hstep, voffB); PG8_STAGE(PG8_SA(0, 0), a2, voffA);
;             PG8_WAIT_V(8); PG8_WAIT_L(0); PG8_BAR; PG8_MMA(1, 0, At, B0); PG8_MMA(1, 1, At, B1); PG8_BAR; PG8_SCHED;
.LBB0_1244:
	s_add_u32 s34, s70, 0xfff80080
	s_addc_u32 s35, s71, -1
	s_add_i32 s68, 0, 0x10000
	s_cmp_eq_u32 s57, 28
	s_cselect_b32 s73, s37, s35
	s_cselect_b32 s72, s49, s34
	v_add_u32_e32 v144, s68, v147
	s_cselect_b32 s35, s31, s56
	s_cselect_b32 s34, s52, s53
	s_add_i32 s76, 0, 0x14000
	ds_read_b128 v[140:143], v144
	ds_read_b128 v[150:153], v144 offset:1024
	ds_read_b128 v[154:157], v144 offset:2048
	ds_read_b128 v[158:161], v144 offset:3072
	v_add_u32_e32 v144, s76, v147
	ds_read_b128 v[162:165], v144
	ds_read_b128 v[166:169], v144 offset:1024
	ds_read_b128 v[170:173], v144 offset:2048
	ds_read_b128 v[174:177], v144 offset:3072
	v_lshl_add_u64 v[144:145], s[70:71], 0, v[136:137]
	s_add_i32 m0, s3, 0xc000
	ds_read_b128 v[178:181], v149
	ds_read_b128 v[182:185], v149 offset:1024
	ds_read_b128 v[186:189], v149 offset:2048
	ds_read_b128 v[202:205], v149 offset:3072
	ds_read_b128 v[206:209], v149 offset:4096
	ds_read_b128 v[210:213], v149 offset:5120
	ds_read_b128 v[214:217], v149 offset:6144
	ds_read_b128 v[218:221], v149 offset:7168
	global_load_lds_dwordx4 v[144:145], off
	v_lshl_add_u64 v[144:145], s[70:71], 0, v[138:139]
	s_add_i32 m0, s3, 0xe000
	s_nop 0
	global_load_lds_dwordx4 v[144:145], off
	s_waitcnt vmcnt(8)
	s_waitcnt lgkmcnt(0)
	s_barrier
	s_setprio 1
	s_waitcnt lgkmcnt(0)
	v_mfma_f32_16x16x32_bf16 v[124:127], v[140:143], v[178:181], v[124:127]
	v_mfma_f32_16x16x32_bf16 v[120:123], v[154:157], v[178:181], v[120:123]
	v_mfma_f32_16x16x32_bf16 v[108:111], v[140:143], v[186:189], v[108:111]
	v_mfma_f32_16x16x32_bf16 v[104:107], v[154:157], v[186:189], v[104:107]
	v_mfma_f32_16x16x32_bf16 v[92:95], v[140:143], v[206:209], v[92:95]
	v_mfma_f32_16x16x32_bf16 v[88:91], v[154:157], v[206:209], v[88:91]
	v_mfma_f32_16x16x32_bf16 v[76:79], v[140:143], v[214:217], v[76:79]
	v_mfma_f32_16x16x32_bf16 v[72:75], v[154:157], v[214:217], v[72:75]
	v_mfma_f32_16x16x32_bf16 v[124:127], v[150:153], v[182:185], v[124:127]
	v_mfma_f32_16x16x32_bf16 v[120:123], v[158:161], v[182:185], v[120:123]
	v_mfma_f32_16x16x32_bf16 v[108:111], v[150:153], v[202:205], v[108:111]
	v_mfma_f32_16x16x32_bf16 v[104:107], v[158:161], v[202:205], v[104:107]
	v_mfma_f32_16x16x32_bf16 v[92:95], v[150:153], v[210:213], v[92:95]
	v_mfma_f32_16x16x32_bf16 v[88:91], v[158:161], v[210:213], v[88:91]
	v_mfma_f32_16x16x32_bf16 v[76:79], v[150:153], v[218:221], v[76:79]
	v_mfma_f32_16x16x32_bf16 v[72:75], v[158:161], v[218:221], v[72:75]
	v_mfma_f32_16x16x32_bf16 v[116:119], v[162:165], v[178:181], v[116:119]
	v_mfma_f32_16x16x32_bf16 v[112:115], v[170:173], v[178:181], v[112:115]
	v_mfma_f32_16x16x32_bf16 v[100:103], v[162:165], v[186:189], v[100:103]
	v_mfma_f32_16x16x32_bf16 v[96:99], v[170:173], v[186:189], v[96:99]
	v_mfma_f32_16x16x32_bf16 v[84:87], v[162:165], v[206:209], v[84:87]
	v_mfma_f32_16x16x32_bf16 v[80:83], v[170:173], v[206:209], v[80:83]
	v_mfma_f32_16x16x32_bf16 v[68:71], v[162:165], v[214:217], v[68:71]
	v_mfma_f32_16x16x32_bf16 v[64:67], v[170:173], v[214:217], v[64:67]
	v_mfma_f32_16x16x32_bf16 v[116:119], v[166:169], v[182:185], v[116:119]
	v_mfma_f32_16x16x32_bf16 v[112:115], v[174:177], v[182:185], v[112:115]
	v_mfma_f32_16x16x32_bf16 v[100:103], v[166:169], v[202:205], v[100:103]
	v_mfma_f32_16x16x32_bf16 v[96:99], v[174:177], v[202:205], v[96:99]
	v_mfma_f32_16x16x32_bf16 v[84:87], v[166:169], v[210:213], v[84:87]
	v_mfma_f32_16x16x32_bf16 v[80:83], v[174:177], v[210:213], v[80:83]
	v_mfma_f32_16x16x32_bf16 v[68:71], v[166:169], v[218:221], v[68:71]
	v_mfma_f32_16x16x32_bf16 v[64:67], v[174:177], v[218:221], v[64:67]
	s_setprio 0
	s_barrier
	s_add_i32 s68, s68, s2
	v_lshl_add_u64 v[144:145], s[34:35], 0, v[132:133]
	s_mov_b32 m0, s68
	ds_read_b128 v[178:181], v149 offset:16384
	ds_read_b128 v[182:185], v149 offset:17408
	ds_read_b128 v[186:189], v149 offset:18432
	ds_read_b128 v[202:205], v149 offset:19456
	ds_read_b128 v[206:209], v149 offset:20480
	ds_read_b128 v[210:213], v149 offset:21504
	ds_read_b128 v[214:217], v149 offset:22528
	ds_read_b128 v[218:221], v149 offset:23552
	global_load_lds_dwordx4 v[144:145], off
	s_add_i32 m0, s68, 0x2000
	s_add_u32 s74, s34, 0x80000
	v_lshl_add_u64 v[190:191], s[34:35], 0, v[128:129]
	s_addc_u32 s75, s35, 0
	s_add_i32 s68, s76, s2
	global_load_lds_dwordx4 v[190:191], off
	v_lshl_add_u64 v[194:195], s[74:75], 0, v[132:133]
	s_mov_b32 m0, s68
	v_lshl_add_u64 v[196:197], s[72:73], 0, v[130:131]
	global_load_lds_dwordx4 v[194:195], off
	v_lshl_add_u64 v[194:195], s[74:75], 0, v[128:129]
	s_add_i32 m0, s68, 0x2000
	s_nop 0
	global_load_lds_dwordx4 v[194:195], off
	v_lshl_add_u64 v[194:195], s[72:73], 0, v[134:135]
	s_mov_b32 m0, s3
	s_nop 0
	global_load_lds_dwordx4 v[194:195], off
	s_mov_b32 m0, s22
	s_nop 0
	global_load_lds_dwordx4 v[196:197], off
	s_waitcnt vmcnt(8)
	s_waitcnt lgkmcnt(0)
	s_barrier
; #define PG8_STAGE(bufoff, gbase, voff) do { _Pragma("unroll") for (int _i = 0; _i < 2; ++_i) \
;         __builtin_amdgcn_global_load_lds((const unsigned*)((const char*)(gbase) + (voff)[_i]), (PG8_LAS unsigned*)(lds + (bufoff) + ldsw + _i * 8192), 16, 0, 0); } while (0)
; #define PG8_LDA(dst, b, h) do { _Pragma("unroll") for (int m = 0; m < 4; ++m) _Pragma("unroll") for (int k = 0; k < 2; ++k) dst[m][k] = *(const PG8_LAS bf16x8*)(lds + PG8_SA(b, h) + aoff + m * 2048 + k * 1024); } while (0)
; #define PG8_LDB(dst, b, h) do { _Pragma("unroll") for (int n = 0; n < 2; ++n) _Pragma("unroll") for (int k = 0; k < 2; ++k) dst[n][k] = *(const PG8_LAS bf16x8*)(lds + PG8_SB(b, h) + boff + n * 2048 + k * 1024); } while (0)
; #define PG8_MMA(ai, bj, At, Bt) do { __builtin_amdgcn_s_setprio(1); _Pragma("unroll") for (int m = 0; m < 4; ++m) _Pragma("unroll") for (int n = 0; n < 2; ++n) _Pragma("unroll") for (int k = 0; k < 2; ++k) \
;         acc[ai][bj][m][n] = __builtin_amdgcn_mfma_f32_16x16x32_bf16(Bt[n][k], At[m][k], acc[ai][bj][m][n], 0, 0, 0); __builtin_amdgcn_s_setprio(0); } while (0)
; #define PG8_WAIT_V(n) asm volatile("s_waitcnt vmcnt(" #n ")" ::: "memory")
; #define PG8_WAIT_L(n) asm volatile("s_waitcnt lgkmcnt(" #n ")" ::: "memory")
; #define PG8_BAR __builtin_amdgcn_s_barrier()
; #define PG8_SCHED __builtin_amdgcn_sched_barrier(0)
; template <class Epi, class Sched, bool ALIGN_EPI = false, bool SP2 = false>
; __device__ __forceinline__ void gemm_phase(PG8_LAS unsigned char* lds, const Gemm g, const Sched& S, const Epi& E, const int wid0) {
;     ...
;             PG8_WAIT_V(8); PG8_WAIT_L(0); PG8_BAR; PG8_MMA(1, 0, At, B0); PG8_MMA(1, 1, At, B1); PG8_BAR; PG8_SCHED;
;             PG8_LDB(B0, 1, 0); PG8_LDB(B1, 1, 1); PG8_SCHED; PG8_LDA(At, 1, 0); PG8_STAGE(PG8_SA(0, 1), a2 + hstep, voffA);
;             PG8_WAIT_V(8); PG8_WAIT_L(0); PG8_BAR; PG8_MMA(0, 0, At, B0); PG8_MMA(0, 1, At, B1); PG8_BAR; PG8_SCHED;
	s_setprio 1
	s_waitcnt lgkmcnt(0)
	v_mfma_f32_16x16x32_bf16 v[60:63], v[140:143], v[178:181], v[60:63]
	v_mfma_f32_16x16x32_bf16 v[56:59], v[154:157], v[178:181], v[56:59]
	v_mfma_f32_16x16x32_bf16 v[44:47], v[140:143], v[186:189], v[44:47]
	v_mfma_f32_16x16x32_bf16 v[40:43], v[154:157], v[186:189], v[40:43]
	v_mfma_f32_16x16x32_bf16 v[28:31], v[140:143], v[206:209], v[28:31]
	v_mfma_f32_16x16x32_bf16 v[24:27], v[154:157], v[206:209], v[24:27]
	v_mfma_f32_16x16x32_bf16 v[12:15], v[140:143], v[214:217], v[12:15]
	v_mfma_f32_16x16x32_bf16 v[8:11], v[154:157], v[214:217], v[8:11]
	v_mfma_f32_16x16x32_bf16 v[60:63], v[150:153], v[182:185], v[60:63]
	v_mfma_f32_16x16x32_bf16 v[56:59], v[158:161], v[182:185], v[56:59]
	v_mfma_f32_16x16x32_bf16 v[44:47], v[150:153], v[202:205], v[44:47]
	v_mfma_f32_16x16x32_bf16 v[40:43], v[158:161], v[202:205], v[40:43]
	v_mfma_f32_16x16x32_bf16 v[28:31], v[150:153], v[210:213], v[28:31]
	v_mfma_f32_16x16x32_bf16 v[24:27], v[158:161], v[210:213], v[24:27]
	v_mfma_f32_16x16x32_bf16 v[12:15], v[150:153], v[218:221], v[12:15]
	v_mfma_f32_16x16x32_bf16 v[8:11], v[158:161], v[218:221], v[8:11]
	v_mfma_f32_16x16x32_bf16 v[52:55], v[162:165], v[178:181], v[52:55]
	v_mfma_f32_16x16x32_bf16 v[48:51], v[170:173], v[178:181], v[48:51]
	v_mfma_f32_16x16x32_bf16 v[36:39], v[162:165], v[186:189], v[36:39]
	v_mfma_f32_16x16x32_bf16 v[32:35], v[170:173], v[186:189], v[32:35]
	v_mfma_f32_16x16x32_bf16 v[20:23], v[162:165], v[206:209], v[20:23]
	v_mfma_f32_16x16x32_bf16 v[16:19], v[170:173], v[206:209], v[16:19]
	v_mfma_f32_16x16x32_bf16 v[4:7], v[162:165], v[214:217], v[4:7]
	v_mfma_f32_16x16x32_bf16 v[0:3], v[170:173], v[214:217], v[0:3]
	v_mfma_f32_16x16x32_bf16 v[52:55], v[166:169], v[182:185], v[52:55]
	v_mfma_f32_16x16x32_bf16 v[48:51], v[174:177], v[182:185], v[48:51]
	v_mfma_f32_16x16x32_bf16 v[36:39], v[166:169], v[202:205], v[36:39]
	v_mfma_f32_16x16x32_bf16 v[32:35], v[174:177], v[202:205], v[32:35]
	v_mfma_f32_16x16x32_bf16 v[20:23], v[166:169], v[210:213], v[20:23]
	v_mfma_f32_16x16x32_bf16 v[16:19], v[174:177], v[210:213], v[16:19]
	v_mfma_f32_16x16x32_bf16 v[4:7], v[166:169], v[218:221], v[4:7]
	v_mfma_f32_16x16x32_bf16 v[0:3], v[174:177], v[218:221], v[0:3]
	s_setprio 0
	s_barrier
	s_add_i32 s68, 0, 0x18000
	s_add_i32 s74, 0, 0x1c000
	v_add_u32_e32 v158, s68, v147
	v_add_u32_e32 v174, s74, v147
	ds_read_b128 v[140:143], v158
	ds_read_b128 v[150:153], v158 offset:1024
	ds_read_b128 v[154:157], v158 offset:2048
	ds_read_b128 v[158:161], v158 offset:3072
	ds_read_b128 v[162:165], v174
	ds_read_b128 v[166:169], v174 offset:1024
	ds_read_b128 v[170:173], v174 offset:2048
	ds_read_b128 v[174:177], v174 offset:3072
	s_add_u32 s72, s72, 0x80000
	s_addc_u32 s73, s73, 0
	s_mov_b32 m0, s23
	v_lshl_add_u64 v[222:223], s[72:73], 0, v[134:135]
	ds_read_b128 v[178:181], v149 offset:32768
	ds_read_b128 v[182:185], v149 offset:33792
	ds_read_b128 v[186:189], v149 offset:34816
	ds_read_b128 v[202:205], v149 offset:35840
	ds_read_b128 v[206:209], v149 offset:36864
	ds_read_b128 v[210:213], v149 offset:37888
	ds_read_b128 v[214:217], v149 offset:38912
	ds_read_b128 v[218:221], v149 offset:39936
	global_load_lds_dwordx4 v[222:223], off
	v_lshl_add_u64 v[222:223], s[72:73], 0, v[130:131]
	s_mov_b32 m0, s77
	s_nop 0
	global_load_lds_dwordx4 v[222:223], off
	s_waitcnt vmcnt(8)
	s_waitcnt lgkmcnt(0)
	s_barrier
	s_setprio 1
	s_waitcnt lgkmcnt(0)
	v_mfma_f32_16x16x32_bf16 v[124:127], v[140:143], v[178:181], v[124:127]
	v_mfma_f32_16x16x32_bf16 v[120:123], v[154:157], v[178:181], v[120:123]
	v_mfma_f32_16x16x32_bf16 v[108:111], v[140:143], v[186:189], v[108:111]
	v_mfma_f32_16x16x32_bf16 v[104:107], v[154:157], v[186:189], v[104:107]
	v_mfma_f32_16x16x32_bf16 v[92:95], v[140:143], v[206:209], v[92:95]
	v_mfma_f32_16x16x32_bf16 v[88:91], v[154:157], v[206:209], v[88:91]
	v_mfma_f32_16x16x32_bf16 v[76:79], v[140:143], v[214:217], v[76:79]
	v_mfma_f32_16x16x32_bf16 v[72:75], v[154:157], v[214:217], v[72:75]
	v_mfma_f32_16x16x32_bf16 v[124:127], v[150:153], v[182:185], v[124:127]
	v_mfma_f32_16x16x32_bf16 v[120:123], v[158:161], v[182:185], v[120:123]
	v_mfma_f32_16x16x32_bf16 v[108:111], v[150:153], v[202:205], v[108:111]
	v_mfma_f32_16x16x32_bf16 v[104:107], v[158:161], v[202:205], v[104:107]
	v_mfma_f32_16x16x32_bf16 v[92:95], v[150:153], v[210:213], v[92:95]
	v_mfma_f32_16x16x32_bf16 v[88:91], v[158:161], v[210:213], v[88:91]
	v_mfma_f32_16x16x32_bf16 v[76:79], v[150:153], v[218:221], v[76:79]
	v_mfma_f32_16x16x32_bf16 v[72:75], v[158:161], v[218:221], v[72:75]
	v_mfma_f32_16x16x32_bf16 v[116:119], v[162:165], v[178:181], v[116:119]
	v_mfma_f32_16x16x32_bf16 v[112:115], v[170:173], v[178:181], v[112:115]
	v_mfma_f32_16x16x32_bf16 v[100:103], v[162:165], v[186:189], v[100:103]
	v_mfma_f32_16x16x32_bf16 v[96:99], v[170:173], v[186:189], v[96:99]
	v_mfma_f32_16x16x32_bf16 v[84:87], v[162:165], v[206:209], v[84:87]
	v_mfma_f32_16x16x32_bf16 v[80:83], v[170:173], v[206:209], v[80:83]
	v_mfma_f32_16x16x32_bf16 v[68:71], v[162:165], v[214:217], v[68:71]
	v_mfma_f32_16x16x32_bf16 v[64:67], v[170:173], v[214:217], v[64:67]
	v_mfma_f32_16x16x32_bf16 v[116:119], v[166:169], v[182:185], v[116:119]
	v_mfma_f32_16x16x32_bf16 v[112:115], v[174:177], v[182:185], v[112:115]
	v_mfma_f32_16x16x32_bf16 v[100:103], v[166:169], v[202:205], v[100:103]
	v_mfma_f32_16x16x32_bf16 v[96:99], v[174:177], v[202:205], v[96:99]
	v_mfma_f32_16x16x32_bf16 v[84:87], v[166:169], v[210:213], v[84:87]
	v_mfma_f32_16x16x32_bf16 v[80:83], v[174:177], v[210:213], v[80:83]
	v_mfma_f32_16x16x32_bf16 v[68:71], v[166:169], v[218:221], v[68:71]
	v_mfma_f32_16x16x32_bf16 v[64:67], v[174:177], v[218:221], v[64:67]
	s_setprio 0
	s_barrier
; #define PG8_STAGE(bufoff, gbase, voff) do { _Pragma("unroll") for (int _i = 0; _i < 2; ++_i) \
;         __builtin_amdgcn_global_load_lds((const unsigned*)((const char*)(gbase) + (voff)[_i]), (PG8_LAS unsigned*)(lds + (bufoff) + ldsw + _i * 8192), 16, 0, 0); } while (0)
; #define PG8_LDA(dst, b, h) do { _Pragma("unroll") for (int m = 0; m < 4; ++m) _Pragma("unroll") for (int k = 0; k < 2; ++k) dst[m][k] = *(const PG8_LAS bf16x8*)(lds + PG8_SA(b, h) + aoff + m * 2048 + k * 1024); } while (0)
; #define PG8_MMA(ai, bj, At, Bt) do { __builtin_amdgcn_s_setprio(1); _Pragma("unroll") for (int m = 0; m < 4; ++m) _Pragma("unroll") for (int n = 0; n < 2; ++n) _Pragma("unroll") for (int k = 0; k < 2; ++k) \
;         acc[ai][bj][m][n] = __builtin_amdgcn_mfma_f32_16x16x32_bf16(Bt[n][k], At[m][k], acc[ai][bj][m][n], 0, 0, 0); __builtin_amdgcn_s_setprio(0); } while (0)
; #define PG8_WAIT_V(n) asm volatile("s_waitcnt vmcnt(" #n ")" ::: "memory")
; #define PG8_WAIT_L(n) asm volatile("s_waitcnt lgkmcnt(" #n ")" ::: "memory")
; #define PG8_BAR __builtin_amdgcn_s_barrier()
; #define PG8_SCHED __builtin_amdgcn_sched_barrier(0)
; template <class Epi, class Sched, bool ALIGN_EPI = false, bool SP2 = false>
; __device__ __forceinline__ void gemm_phase(PG8_LAS unsigned char* lds, const Gemm g, const Sched& S, const Epi& E, const int wid0) {
;     ...
;             PG8_LDA(At, 1, 1); PG8_STAGE(PG8_SB(1, 0), b3, voffB); PG8_STAGE(PG8_SB(1, 1), b3 + hstep, voffB); PG8_STAGE(PG8_SA(1, 0), a3, voffA);
;             PG8_WAIT_V(8); PG8_WAIT_L(0); PG8_BAR; PG8_MMA(1, 0, At, B0); PG8_MMA(1, 1, At, B1); PG8_BAR; PG8_SCHED;
;     ...
;         if constexpr (ALIGN_EPI) { if (wr == 0) PG8_BAR; }
	s_add_i32 s68, s68, s2
	v_lshl_add_u64 v[144:145], v[144:145], 0, s[54:55]
	s_mov_b32 m0, s68
	ds_read_b128 v[178:181], v149 offset:49152
	ds_read_b128 v[182:185], v149 offset:50176
	ds_read_b128 v[186:189], v149 offset:51200
	ds_read_b128 v[202:205], v149 offset:52224
	ds_read_b128 v[206:209], v149 offset:53248
	ds_read_b128 v[210:213], v149 offset:54272
	ds_read_b128 v[214:217], v149 offset:55296
	ds_read_b128 v[218:221], v149 offset:56320
	global_load_lds_dwordx4 v[144:145], off
	s_add_i32 m0, s68, 0x2000
	s_add_u32 s34, s34, 0x80080
	v_lshl_add_u64 v[144:145], v[190:191], 0, s[54:55]
	s_addc_u32 s35, s35, 0
	s_add_i32 s68, s74, s2
	global_load_lds_dwordx4 v[144:145], off
	v_lshl_add_u64 v[144:145], s[34:35], 0, v[132:133]
	s_mov_b32 m0, s68
	s_nop 0
	global_load_lds_dwordx4 v[144:145], off
	v_lshl_add_u64 v[144:145], s[34:35], 0, v[128:129]
	s_add_i32 m0, s68, 0x2000
	s_nop 0
	global_load_lds_dwordx4 v[144:145], off
	v_lshl_add_u64 v[144:145], v[194:195], 0, s[54:55]
	s_mov_b32 m0, s39
	s_nop 0
	global_load_lds_dwordx4 v[144:145], off
	v_lshl_add_u64 v[144:145], v[196:197], 0, s[54:55]
	s_mov_b32 m0, s40
	s_nop 0
	global_load_lds_dwordx4 v[144:145], off
	s_waitcnt vmcnt(8)
	s_waitcnt lgkmcnt(0)
	s_barrier
	s_setprio 1
	s_waitcnt lgkmcnt(0)
	v_mfma_f32_16x16x32_bf16 v[60:63], v[140:143], v[178:181], v[60:63]
	v_mfma_f32_16x16x32_bf16 v[56:59], v[154:157], v[178:181], v[56:59]
	v_mfma_f32_16x16x32_bf16 v[44:47], v[140:143], v[186:189], v[44:47]
	v_mfma_f32_16x16x32_bf16 v[40:43], v[154:157], v[186:189], v[40:43]
	v_mfma_f32_16x16x32_bf16 v[28:31], v[140:143], v[206:209], v[28:31]
	v_mfma_f32_16x16x32_bf16 v[24:27], v[154:157], v[206:209], v[24:27]
	v_mfma_f32_16x16x32_bf16 v[12:15], v[140:143], v[214:217], v[12:15]
	v_mfma_f32_16x16x32_bf16 v[8:11], v[154:157], v[214:217], v[8:11]
	v_mfma_f32_16x16x32_bf16 v[60:63], v[150:153], v[182:185], v[60:63]
	v_mfma_f32_16x16x32_bf16 v[56:59], v[158:161], v[182:185], v[56:59]
	v_mfma_f32_16x16x32_bf16 v[44:47], v[150:153], v[202:205], v[44:47]
	v_mfma_f32_16x16x32_bf16 v[40:43], v[158:161], v[202:205], v[40:43]
	v_mfma_f32_16x16x32_bf16 v[28:31], v[150:153], v[210:213], v[28:31]
	v_mfma_f32_16x16x32_bf16 v[24:27], v[158:161], v[210:213], v[24:27]
	v_mfma_f32_16x16x32_bf16 v[12:15], v[150:153], v[218:221], v[12:15]
	v_mfma_f32_16x16x32_bf16 v[8:11], v[158:161], v[218:221], v[8:11]
	v_mfma_f32_16x16x32_bf16 v[52:55], v[162:165], v[178:181], v[52:55]
	v_mfma_f32_16x16x32_bf16 v[48:51], v[170:173], v[178:181], v[48:51]
	v_mfma_f32_16x16x32_bf16 v[36:39], v[162:165], v[186:189], v[36:39]
	v_mfma_f32_16x16x32_bf16 v[32:35], v[170:173], v[186:189], v[32:35]
	v_mfma_f32_16x16x32_bf16 v[20:23], v[162:165], v[206:209], v[20:23]
	v_mfma_f32_16x16x32_bf16 v[16:19], v[170:173], v[206:209], v[16:19]
	v_mfma_f32_16x16x32_bf16 v[4:7], v[162:165], v[214:217], v[4:7]
	v_mfma_f32_16x16x32_bf16 v[0:3], v[170:173], v[214:217], v[0:3]
	v_mfma_f32_16x16x32_bf16 v[52:55], v[166:169], v[182:185], v[52:55]
	v_mfma_f32_16x16x32_bf16 v[48:51], v[174:177], v[182:185], v[48:51]
	v_mfma_f32_16x16x32_bf16 v[36:39], v[166:169], v[202:205], v[36:39]
	v_mfma_f32_16x16x32_bf16 v[32:35], v[174:177], v[202:205], v[32:35]
	v_mfma_f32_16x16x32_bf16 v[20:23], v[166:169], v[210:213], v[20:23]
	v_mfma_f32_16x16x32_bf16 v[16:19], v[174:177], v[210:213], v[16:19]
	v_mfma_f32_16x16x32_bf16 v[4:7], v[166:169], v[218:221], v[4:7]
	v_mfma_f32_16x16x32_bf16 v[0:3], v[174:177], v[218:221], v[0:3]
	s_setprio 0
	s_barrier
	s_add_i32 s57, s57, 2
	s_add_u32 s70, s70, 0x100
	s_addc_u32 s71, s71, 0
	s_add_u32 s53, s53, 0x100
	s_addc_u32 s56, s56, 0
	s_cmp_gt_u32 s57, 29
	s_cbranch_scc0 .LBB0_1244
	s_and_b64 vcc, exec, s[10:11]
	s_cbranch_vccz .LBB0_1247
	s_barrier
